# hot loop branch targets (GEMM K-loops, NSA/MLA tile blocks) aligned to 64 bytes
# baseline (speedup 1.0000x reference)
; #define PG8_STAGE(bufoff, gbase, voff) do { const char* _gb = (const char*)(gbase); asm volatile("" : "+s"(_gb)); _Pragma("unroll") for (int _i = 0; _i < 2; ++_i) { \
;         unsigned _vo = (voff)[_i]; asm volatile("" : "+v"(_vo));     \
;         __builtin_amdgcn_global_load_lds((const unsigned*)(_gb + _vo), (LAS unsigned*)(lds + (bufoff) + ldsw + _i * 8192), 16, 0, 0); } } while (0)
; #define PG8_LDA(dst, b, h) do { _Pragma("unroll") for (int m = 0; m < 4; ++m) _Pragma("unroll") for (int k = 0; k < 2; ++k) dst[m][k] = *(const LAS bf16x8*)(lds + PG8_SA(b, h) + aoff + m * 2048 + k * 1024); } while (0)
; #define PG8_LDB(dst, b, h) do { _Pragma("unroll") for (int n = 0; n < 2; ++n) _Pragma("unroll") for (int k = 0; k < 2; ++k) dst[n][k] = *(const LAS bf16x8*)(lds + PG8_SB(b, h) + boff + n * 2048 + k * 1024); } while (0)
; #define PG8_MMA(ai, bj, At, Bt) do { __builtin_amdgcn_s_setprio(1); _Pragma("unroll") for (int m = 0; m < 4; ++m) _Pragma("unroll") for (int n = 0; n < 2; ++n) _Pragma("unroll") for (int k = 0; k < 2; ++k) \
;         acc[ai][bj][m][n] = __builtin_amdgcn_mfma_f32_16x16x32_bf16(Bt[n][k], At[m][k], acc[ai][bj][m][n], 0, 0, 0); __builtin_amdgcn_s_setprio(0); } while (0)
; #define PG8_WAIT_V(n) asm volatile("s_waitcnt vmcnt(" #n ")" ::: "memory")
; #define PG8_WAIT_L(n) asm volatile("s_waitcnt lgkmcnt(" #n ")" ::: "memory")
; #define PG8_BAR __builtin_amdgcn_s_barrier()
; #define PG8_SCHED __builtin_amdgcn_sched_barrier(0)
; template <class Epi, class Sched>
; DI void gemm_phase(int wv, LAS unsigned char* lds, const Gemm g, const Sched& S, const Epi& E) {
;     ...
;         for (int t = 0; t < nt; t += 2) {
;             const bool last = (t == nt - 2);
;             const char* a1 = cA + (size_t)(t + 1) * kstep;
;             const char* a2 = last ? nA : cA + (size_t)(t + 2) * kstep; const char* b2 = last ? nB : cB + (size_t)(t + 2) * kstep;
;             const char* a3 = a2 + kstep; const char* b3 = b2 + kstep;
;             PG8_LDB(B0, 0, 0); PG8_LDB(B1, 0, 1); PG8_SCHED; PG8_LDA(At, 0, 0); PG8_STAGE(PG8_SA(1, 1), a1 + hstepA, voffA);
;             PG8_WAIT_V(8); PG8_WAIT_L(0); PG8_BAR; PG8_MMA(0, 0, At, B0); PG8_MMA(0, 1, At, B1); PG8_BAR; PG8_SCHED;
;             PG8_LDA(At, 0, 1); PG8_STAGE(PG8_SB(0, 0), b2, voffB); PG8_STAGE(PG8_SB(0, 1), b2 + hstepB, voffB); PG8_STAGE(PG8_SA(0, 0), a2, voffA);
.LBB0_1816:
	s_ashr_i32 s15, s14, 31
	s_lshl_b64 s[18:19], s[14:15], 19
	s_add_u32 s18, s34, s18
	s_addc_u32 s19, s35, s19
	s_and_b64 s[20:21], s[24:25], exec
	s_cselect_b32 s1, s19, s3
	s_cselect_b32 s23, s18, s2
	s_ashr_i32 s17, s16, 31
	s_lshl_b64 s[20:21], s[16:17], 19
	s_add_u32 s20, s36, s20
	s_addc_u32 s21, s37, s21
	s_and_b64 s[28:29], s[24:25], exec
	s_cselect_b32 s17, s21, s27
	s_cselect_b32 s55, s20, s26
	s_add_u32 s56, s26, 0x100
	s_addc_u32 s57, s27, 0
	s_add_u32 s2, s2, 0x40080
	s_addc_u32 s3, s3, 0
	s_mov_b32 s60, -2
	s_add_u32 s26, s2, 0xfffc0080
	s_addc_u32 s27, s3, -1
	s_cmp_eq_u32 s60, 12
	s_cselect_b32 s30, s23, s26
	s_cselect_b32 s31, s1, s27
	s_cselect_b32 s28, s55, s56
	s_cselect_b32 s29, s17, s57
	s_add_u32 s26, s30, 0x80
	s_addc_u32 s27, s31, 0
	s_add_i32 s61, 0, 0x10000
	s_add_i32 s66, 0, 0x14000
	v_add_u32_e32 v142, s61, v0
	v_add_u32_e32 v158, s66, v0
	ds_read_b128 v[98:101], v142
	ds_read_b128 v[118:121], v142 offset:1024
	ds_read_b128 v[138:141], v142 offset:2048
	ds_read_b128 v[142:145], v142 offset:3072
	ds_read_b128 v[146:149], v158
	ds_read_b128 v[150:153], v158 offset:1024
	ds_read_b128 v[154:157], v158 offset:2048
	ds_read_b128 v[158:161], v158 offset:3072
	s_mov_b64 s[64:65], s[2:3]
	v_mov_b32_e32 v177, v170
	ds_read_b128 v[162:165], v176
	ds_read_b128 v[166:169], v176 offset:1024
	ds_read_b128 v[178:181], v176 offset:2048
	ds_read_b128 v[182:185], v176 offset:3072
	ds_read_b128 v[186:189], v176 offset:4096
	ds_read_b128 v[190:193], v176 offset:5120
	ds_read_b128 v[194:197], v176 offset:6144
	ds_read_b128 v[198:201], v176 offset:7168
	s_add_i32 m0, s46, 0xc000
	s_nop 0
	global_load_lds_dwordx4 v177, s[64:65]
	v_mov_b32_e32 v177, v172
	s_add_i32 m0, s46, 0xe000
	s_nop 0
	global_load_lds_dwordx4 v177, s[64:65]
	s_waitcnt vmcnt(8)
	s_waitcnt lgkmcnt(0)
	s_barrier
	s_setprio 1
	s_waitcnt lgkmcnt(0)
	v_mfma_f32_16x16x32_bf16 v[134:137], v[98:101], v[162:165], 0
	v_mfma_f32_16x16x32_bf16 v[130:133], v[138:141], v[162:165], 0
	v_mfma_f32_16x16x32_bf16 v[114:117], v[98:101], v[178:181], 0
	v_mfma_f32_16x16x32_bf16 v[110:113], v[138:141], v[178:181], 0
	v_mfma_f32_16x16x32_bf16 v[94:97], v[98:101], v[186:189], 0
	v_mfma_f32_16x16x32_bf16 v[90:93], v[138:141], v[186:189], 0
	v_mfma_f32_16x16x32_bf16 v[78:81], v[98:101], v[194:197], 0
	v_mfma_f32_16x16x32_bf16 v[74:77], v[138:141], v[194:197], 0
	v_mfma_f32_16x16x32_bf16 v[134:137], v[118:121], v[166:169], v[134:137]
	v_mfma_f32_16x16x32_bf16 v[130:133], v[142:145], v[166:169], v[130:133]
	v_mfma_f32_16x16x32_bf16 v[114:117], v[118:121], v[182:185], v[114:117]
	v_mfma_f32_16x16x32_bf16 v[110:113], v[142:145], v[182:185], v[110:113]
	v_mfma_f32_16x16x32_bf16 v[94:97], v[118:121], v[190:193], v[94:97]
	v_mfma_f32_16x16x32_bf16 v[90:93], v[142:145], v[190:193], v[90:93]
	v_mfma_f32_16x16x32_bf16 v[78:81], v[118:121], v[198:201], v[78:81]
	v_mfma_f32_16x16x32_bf16 v[74:77], v[142:145], v[198:201], v[74:77]
	s_setprio 0
	s_setprio 1
	v_mfma_f32_16x16x32_bf16 v[126:129], v[146:149], v[162:165], 0
	v_mfma_f32_16x16x32_bf16 v[122:125], v[154:157], v[162:165], 0
	v_mfma_f32_16x16x32_bf16 v[106:109], v[146:149], v[178:181], 0
	v_mfma_f32_16x16x32_bf16 v[102:105], v[154:157], v[178:181], 0
	v_mfma_f32_16x16x32_bf16 v[86:89], v[146:149], v[186:189], 0
	v_mfma_f32_16x16x32_bf16 v[82:85], v[154:157], v[186:189], 0
	v_mfma_f32_16x16x32_bf16 v[70:73], v[146:149], v[194:197], 0
	v_mfma_f32_16x16x32_bf16 v[66:69], v[154:157], v[194:197], 0
	v_mfma_f32_16x16x32_bf16 v[126:129], v[150:153], v[166:169], v[126:129]
	v_mfma_f32_16x16x32_bf16 v[122:125], v[158:161], v[166:169], v[122:125]
	v_mfma_f32_16x16x32_bf16 v[106:109], v[150:153], v[182:185], v[106:109]
	v_mfma_f32_16x16x32_bf16 v[102:105], v[158:161], v[182:185], v[102:105]
	v_mfma_f32_16x16x32_bf16 v[86:89], v[150:153], v[190:193], v[86:89]
	v_mfma_f32_16x16x32_bf16 v[82:85], v[158:161], v[190:193], v[82:85]
	v_mfma_f32_16x16x32_bf16 v[70:73], v[150:153], v[198:201], v[70:73]
	v_mfma_f32_16x16x32_bf16 v[66:69], v[158:161], v[198:201], v[66:69]
	s_setprio 0
	s_barrier
	s_mov_b64 s[64:65], s[28:29]
	v_mov_b32_e32 v177, v171
	s_add_i32 s61, s61, s38
	ds_read_b128 v[162:165], v176 offset:16384
	ds_read_b128 v[166:169], v176 offset:17408
	ds_read_b128 v[178:181], v176 offset:18432
	ds_read_b128 v[182:185], v176 offset:19456
	ds_read_b128 v[186:189], v176 offset:20480
	ds_read_b128 v[190:193], v176 offset:21504
	ds_read_b128 v[194:197], v176 offset:22528
	ds_read_b128 v[198:201], v176 offset:23552
	s_mov_b32 m0, s61
	s_nop 0
	global_load_lds_dwordx4 v177, s[64:65]
	v_mov_b32_e32 v177, v173
	s_add_i32 m0, s61, 0x2000
	s_nop 0
	global_load_lds_dwordx4 v177, s[64:65]
	s_add_u32 s64, s28, 0x40000
	s_addc_u32 s65, s29, 0
	v_mov_b32_e32 v177, v171
	s_add_i32 s61, s66, s38
	s_mov_b32 m0, s61
	s_nop 0
	global_load_lds_dwordx4 v177, s[64:65]
	v_mov_b32_e32 v177, v173
	s_add_i32 m0, s61, 0x2000
	s_nop 0
	global_load_lds_dwordx4 v177, s[64:65]
	s_mov_b64 s[64:65], s[30:31]
	v_mov_b32_e32 v177, v170
	s_mov_b32 m0, s46
	s_nop 0
	global_load_lds_dwordx4 v177, s[64:65]
	v_mov_b32_e32 v177, v172
	s_mov_b32 m0, s47
	s_nop 0
	global_load_lds_dwordx4 v177, s[64:65]
	s_waitcnt vmcnt(8)
	s_waitcnt lgkmcnt(0)
	s_barrier
; #define PG8_STAGE(bufoff, gbase, voff) do { const char* _gb = (const char*)(gbase); asm volatile("" : "+s"(_gb)); _Pragma("unroll") for (int _i = 0; _i < 2; ++_i) { \
;         unsigned _vo = (voff)[_i]; asm volatile("" : "+v"(_vo));     \
;         __builtin_amdgcn_global_load_lds((const unsigned*)(_gb + _vo), (LAS unsigned*)(lds + (bufoff) + ldsw + _i * 8192), 16, 0, 0); } } while (0)
; #define PG8_LDA(dst, b, h) do { _Pragma("unroll") for (int m = 0; m < 4; ++m) _Pragma("unroll") for (int k = 0; k < 2; ++k) dst[m][k] = *(const LAS bf16x8*)(lds + PG8_SA(b, h) + aoff + m * 2048 + k * 1024); } while (0)
; #define PG8_LDB(dst, b, h) do { _Pragma("unroll") for (int n = 0; n < 2; ++n) _Pragma("unroll") for (int k = 0; k < 2; ++k) dst[n][k] = *(const LAS bf16x8*)(lds + PG8_SB(b, h) + boff + n * 2048 + k * 1024); } while (0)
; #define PG8_MMA(ai, bj, At, Bt) do { __builtin_amdgcn_s_setprio(1); _Pragma("unroll") for (int m = 0; m < 4; ++m) _Pragma("unroll") for (int n = 0; n < 2; ++n) _Pragma("unroll") for (int k = 0; k < 2; ++k) \
;         acc[ai][bj][m][n] = __builtin_amdgcn_mfma_f32_16x16x32_bf16(Bt[n][k], At[m][k], acc[ai][bj][m][n], 0, 0, 0); __builtin_amdgcn_s_setprio(0); } while (0)
; #define PG8_WAIT_V(n) asm volatile("s_waitcnt vmcnt(" #n ")" ::: "memory")
; #define PG8_WAIT_L(n) asm volatile("s_waitcnt lgkmcnt(" #n ")" ::: "memory")
; #define PG8_BAR __builtin_amdgcn_s_barrier()
; #define PG8_SCHED __builtin_amdgcn_sched_barrier(0)
; template <class Epi, class Sched>
; DI void gemm_phase(int wv, LAS unsigned char* lds, const Gemm g, const Sched& S, const Epi& E) {
;     ...
;             PG8_WAIT_V(8); PG8_WAIT_L(0); PG8_BAR; PG8_MMA(1, 0, At, B0); PG8_MMA(1, 1, At, B1); PG8_BAR; PG8_SCHED;
;             PG8_LDB(B0, 1, 0); PG8_LDB(B1, 1, 1); PG8_SCHED; PG8_LDA(At, 1, 0); PG8_STAGE(PG8_SA(0, 1), a2 + hstepA, voffA);
;             PG8_WAIT_V(8); PG8_WAIT_L(0); PG8_BAR; PG8_MMA(0, 0, At, B0); PG8_MMA(0, 1, At, B1); PG8_BAR; PG8_SCHED;
	s_setprio 1
	s_waitcnt lgkmcnt(0)
	v_mfma_f32_16x16x32_bf16 v[62:65], v[98:101], v[162:165], 0
	v_mfma_f32_16x16x32_bf16 v[58:61], v[138:141], v[162:165], 0
	v_mfma_f32_16x16x32_bf16 v[46:49], v[98:101], v[178:181], 0
	v_mfma_f32_16x16x32_bf16 v[42:45], v[138:141], v[178:181], 0
	v_mfma_f32_16x16x32_bf16 v[30:33], v[98:101], v[186:189], 0
	v_mfma_f32_16x16x32_bf16 v[26:29], v[138:141], v[186:189], 0
	v_mfma_f32_16x16x32_bf16 v[14:17], v[98:101], v[194:197], 0
	v_mfma_f32_16x16x32_bf16 v[10:13], v[138:141], v[194:197], 0
	v_mfma_f32_16x16x32_bf16 v[62:65], v[118:121], v[166:169], v[62:65]
	v_mfma_f32_16x16x32_bf16 v[58:61], v[142:145], v[166:169], v[58:61]
	v_mfma_f32_16x16x32_bf16 v[46:49], v[118:121], v[182:185], v[46:49]
	v_mfma_f32_16x16x32_bf16 v[42:45], v[142:145], v[182:185], v[42:45]
	v_mfma_f32_16x16x32_bf16 v[30:33], v[118:121], v[190:193], v[30:33]
	v_mfma_f32_16x16x32_bf16 v[26:29], v[142:145], v[190:193], v[26:29]
	v_mfma_f32_16x16x32_bf16 v[14:17], v[118:121], v[198:201], v[14:17]
	v_mfma_f32_16x16x32_bf16 v[10:13], v[142:145], v[198:201], v[10:13]
	s_setprio 0
	s_setprio 1
	v_mfma_f32_16x16x32_bf16 v[54:57], v[146:149], v[162:165], 0
	v_mfma_f32_16x16x32_bf16 v[50:53], v[154:157], v[162:165], 0
	v_mfma_f32_16x16x32_bf16 v[38:41], v[146:149], v[178:181], 0
	v_mfma_f32_16x16x32_bf16 v[34:37], v[154:157], v[178:181], 0
	v_mfma_f32_16x16x32_bf16 v[22:25], v[146:149], v[186:189], 0
	v_mfma_f32_16x16x32_bf16 v[18:21], v[154:157], v[186:189], 0
	v_mfma_f32_16x16x32_bf16 v[6:9], v[146:149], v[194:197], 0
	v_mfma_f32_16x16x32_bf16 v[2:5], v[154:157], v[194:197], 0
	v_mfma_f32_16x16x32_bf16 v[54:57], v[150:153], v[166:169], v[54:57]
	v_mfma_f32_16x16x32_bf16 v[50:53], v[158:161], v[166:169], v[50:53]
	v_mfma_f32_16x16x32_bf16 v[38:41], v[150:153], v[182:185], v[38:41]
	v_mfma_f32_16x16x32_bf16 v[34:37], v[158:161], v[182:185], v[34:37]
	v_mfma_f32_16x16x32_bf16 v[22:25], v[150:153], v[190:193], v[22:25]
	v_mfma_f32_16x16x32_bf16 v[18:21], v[158:161], v[190:193], v[18:21]
	v_mfma_f32_16x16x32_bf16 v[6:9], v[150:153], v[198:201], v[6:9]
	v_mfma_f32_16x16x32_bf16 v[2:5], v[158:161], v[198:201], v[2:5]
	s_setprio 0
	s_barrier
	s_add_i32 s61, 0, 0x18000
	s_add_i32 s64, 0, 0x1c000
	v_add_u32_e32 v142, s61, v0
	v_add_u32_e32 v158, s64, v0
	ds_read_b128 v[98:101], v142
	ds_read_b128 v[118:121], v142 offset:1024
	ds_read_b128 v[138:141], v142 offset:2048
	ds_read_b128 v[142:145], v142 offset:3072
	ds_read_b128 v[146:149], v158
	ds_read_b128 v[150:153], v158 offset:1024
	ds_read_b128 v[154:157], v158 offset:2048
	ds_read_b128 v[158:161], v158 offset:3072
	s_add_u32 s30, s30, 0x40000
	s_addc_u32 s31, s31, 0
	v_mov_b32_e32 v177, v170
	s_mov_b32 m0, s48
	ds_read_b128 v[162:165], v176 offset:32768
	ds_read_b128 v[166:169], v176 offset:33792
	ds_read_b128 v[178:181], v176 offset:34816
	ds_read_b128 v[182:185], v176 offset:35840
	ds_read_b128 v[186:189], v176 offset:36864
	ds_read_b128 v[190:193], v176 offset:37888
	ds_read_b128 v[194:197], v176 offset:38912
	ds_read_b128 v[198:201], v176 offset:39936
	s_nop 0
	global_load_lds_dwordx4 v177, s[30:31]
	v_mov_b32_e32 v177, v172
	s_mov_b32 m0, s49
	s_nop 0
	global_load_lds_dwordx4 v177, s[30:31]
	s_waitcnt vmcnt(8)
	s_waitcnt lgkmcnt(0)
	s_barrier
	s_setprio 1
	s_waitcnt lgkmcnt(0)
	v_mfma_f32_16x16x32_bf16 v[134:137], v[98:101], v[162:165], v[134:137]
	v_mfma_f32_16x16x32_bf16 v[130:133], v[138:141], v[162:165], v[130:133]
	v_mfma_f32_16x16x32_bf16 v[114:117], v[98:101], v[178:181], v[114:117]
	v_mfma_f32_16x16x32_bf16 v[110:113], v[138:141], v[178:181], v[110:113]
	v_mfma_f32_16x16x32_bf16 v[94:97], v[98:101], v[186:189], v[94:97]
	v_mfma_f32_16x16x32_bf16 v[90:93], v[138:141], v[186:189], v[90:93]
	v_mfma_f32_16x16x32_bf16 v[78:81], v[98:101], v[194:197], v[78:81]
	v_mfma_f32_16x16x32_bf16 v[74:77], v[138:141], v[194:197], v[74:77]
	v_mfma_f32_16x16x32_bf16 v[134:137], v[118:121], v[166:169], v[134:137]
	v_mfma_f32_16x16x32_bf16 v[130:133], v[142:145], v[166:169], v[130:133]
	v_mfma_f32_16x16x32_bf16 v[114:117], v[118:121], v[182:185], v[114:117]
	v_mfma_f32_16x16x32_bf16 v[110:113], v[142:145], v[182:185], v[110:113]
	v_mfma_f32_16x16x32_bf16 v[94:97], v[118:121], v[190:193], v[94:97]
	v_mfma_f32_16x16x32_bf16 v[90:93], v[142:145], v[190:193], v[90:93]
	v_mfma_f32_16x16x32_bf16 v[78:81], v[118:121], v[198:201], v[78:81]
	v_mfma_f32_16x16x32_bf16 v[74:77], v[142:145], v[198:201], v[74:77]
	s_setprio 0
	s_setprio 1
	v_mfma_f32_16x16x32_bf16 v[126:129], v[146:149], v[162:165], v[126:129]
	v_mfma_f32_16x16x32_bf16 v[122:125], v[154:157], v[162:165], v[122:125]
	v_mfma_f32_16x16x32_bf16 v[106:109], v[146:149], v[178:181], v[106:109]
	v_mfma_f32_16x16x32_bf16 v[102:105], v[154:157], v[178:181], v[102:105]
	v_mfma_f32_16x16x32_bf16 v[86:89], v[146:149], v[186:189], v[86:89]
	v_mfma_f32_16x16x32_bf16 v[82:85], v[154:157], v[186:189], v[82:85]
	v_mfma_f32_16x16x32_bf16 v[70:73], v[146:149], v[194:197], v[70:73]
	v_mfma_f32_16x16x32_bf16 v[66:69], v[154:157], v[194:197], v[66:69]
	v_mfma_f32_16x16x32_bf16 v[126:129], v[150:153], v[166:169], v[126:129]
	v_mfma_f32_16x16x32_bf16 v[122:125], v[158:161], v[166:169], v[122:125]
	v_mfma_f32_16x16x32_bf16 v[106:109], v[150:153], v[182:185], v[106:109]
	v_mfma_f32_16x16x32_bf16 v[102:105], v[158:161], v[182:185], v[102:105]
	v_mfma_f32_16x16x32_bf16 v[86:89], v[150:153], v[190:193], v[86:89]
	v_mfma_f32_16x16x32_bf16 v[82:85], v[158:161], v[190:193], v[82:85]
	v_mfma_f32_16x16x32_bf16 v[70:73], v[150:153], v[198:201], v[70:73]
	v_mfma_f32_16x16x32_bf16 v[66:69], v[158:161], v[198:201], v[66:69]
	s_setprio 0
	s_barrier
; #define PG8_STAGE(bufoff, gbase, voff) do { const char* _gb = (const char*)(gbase); asm volatile("" : "+s"(_gb)); _Pragma("unroll") for (int _i = 0; _i < 2; ++_i) { \
;         unsigned _vo = (voff)[_i]; asm volatile("" : "+v"(_vo));     \
;         __builtin_amdgcn_global_load_lds((const unsigned*)(_gb + _vo), (LAS unsigned*)(lds + (bufoff) + ldsw + _i * 8192), 16, 0, 0); } } while (0)
; #define PG8_LDA(dst, b, h) do { _Pragma("unroll") for (int m = 0; m < 4; ++m) _Pragma("unroll") for (int k = 0; k < 2; ++k) dst[m][k] = *(const LAS bf16x8*)(lds + PG8_SA(b, h) + aoff + m * 2048 + k * 1024); } while (0)
; #define PG8_MMA(ai, bj, At, Bt) do { __builtin_amdgcn_s_setprio(1); _Pragma("unroll") for (int m = 0; m < 4; ++m) _Pragma("unroll") for (int n = 0; n < 2; ++n) _Pragma("unroll") for (int k = 0; k < 2; ++k) \
;         acc[ai][bj][m][n] = __builtin_amdgcn_mfma_f32_16x16x32_bf16(Bt[n][k], At[m][k], acc[ai][bj][m][n], 0, 0, 0); __builtin_amdgcn_s_setprio(0); } while (0)
; #define PG8_WAIT_V(n) asm volatile("s_waitcnt vmcnt(" #n ")" ::: "memory")
; #define PG8_WAIT_L(n) asm volatile("s_waitcnt lgkmcnt(" #n ")" ::: "memory")
; #define PG8_BAR __builtin_amdgcn_s_barrier()
; #define PG8_SCHED __builtin_amdgcn_sched_barrier(0)
; template <class Epi, class Sched>
; DI void gemm_phase(int wv, LAS unsigned char* lds, const Gemm g, const Sched& S, const Epi& E) {
;     ...
;             PG8_LDA(At, 1, 1); PG8_STAGE(PG8_SB(1, 0), b3, voffB); PG8_STAGE(PG8_SB(1, 1), b3 + hstepB, voffB); PG8_STAGE(PG8_SA(1, 0), a3, voffA);
;             PG8_WAIT_V(8); PG8_WAIT_L(0); PG8_BAR; PG8_MMA(1, 0, At, B0); PG8_MMA(1, 1, At, B1); PG8_BAR; PG8_SCHED;
;         }
	s_add_u32 s30, s28, 0x80
	s_addc_u32 s31, s29, 0
	v_mov_b32_e32 v177, v171
	s_add_i32 s61, s61, s38
	ds_read_b128 v[162:165], v176 offset:49152
	ds_read_b128 v[166:169], v176 offset:50176
	ds_read_b128 v[178:181], v176 offset:51200
	ds_read_b128 v[182:185], v176 offset:52224
	ds_read_b128 v[186:189], v176 offset:53248
	ds_read_b128 v[190:193], v176 offset:54272
	ds_read_b128 v[194:197], v176 offset:55296
	ds_read_b128 v[198:201], v176 offset:56320
	s_mov_b32 m0, s61
	s_nop 0
	global_load_lds_dwordx4 v177, s[30:31]
	v_mov_b32_e32 v177, v173
	s_add_i32 m0, s61, 0x2000
	s_add_u32 s28, s28, 0x40080
	global_load_lds_dwordx4 v177, s[30:31]
	s_addc_u32 s29, s29, 0
	v_mov_b32_e32 v177, v171
	s_add_i32 s30, s64, s38
	s_mov_b32 m0, s30
	s_nop 0
	global_load_lds_dwordx4 v177, s[28:29]
	v_mov_b32_e32 v177, v173
	s_add_i32 m0, s30, 0x2000
	s_nop 0
	global_load_lds_dwordx4 v177, s[28:29]
	v_mov_b32_e32 v177, v170
	s_mov_b32 m0, s50
	s_nop 0
	global_load_lds_dwordx4 v177, s[26:27]
	v_mov_b32_e32 v177, v172
	s_mov_b32 m0, s51
	s_nop 0
	global_load_lds_dwordx4 v177, s[26:27]
	s_waitcnt vmcnt(8)
	s_waitcnt lgkmcnt(0)
	s_barrier
	s_setprio 1
	s_waitcnt lgkmcnt(0)
	v_mfma_f32_16x16x32_bf16 v[62:65], v[98:101], v[162:165], v[62:65]
	v_mfma_f32_16x16x32_bf16 v[58:61], v[138:141], v[162:165], v[58:61]
	v_mfma_f32_16x16x32_bf16 v[46:49], v[98:101], v[178:181], v[46:49]
	v_mfma_f32_16x16x32_bf16 v[42:45], v[138:141], v[178:181], v[42:45]
	v_mfma_f32_16x16x32_bf16 v[30:33], v[98:101], v[186:189], v[30:33]
	v_mfma_f32_16x16x32_bf16 v[26:29], v[138:141], v[186:189], v[26:29]
	v_mfma_f32_16x16x32_bf16 v[14:17], v[98:101], v[194:197], v[14:17]
	v_mfma_f32_16x16x32_bf16 v[10:13], v[138:141], v[194:197], v[10:13]
	v_mfma_f32_16x16x32_bf16 v[62:65], v[118:121], v[166:169], v[62:65]
	v_mfma_f32_16x16x32_bf16 v[58:61], v[142:145], v[166:169], v[58:61]
	v_mfma_f32_16x16x32_bf16 v[46:49], v[118:121], v[182:185], v[46:49]
	v_mfma_f32_16x16x32_bf16 v[42:45], v[142:145], v[182:185], v[42:45]
	v_mfma_f32_16x16x32_bf16 v[30:33], v[118:121], v[190:193], v[30:33]
	v_mfma_f32_16x16x32_bf16 v[26:29], v[142:145], v[190:193], v[26:29]
	v_mfma_f32_16x16x32_bf16 v[14:17], v[118:121], v[198:201], v[14:17]
	v_mfma_f32_16x16x32_bf16 v[10:13], v[142:145], v[198:201], v[10:13]
	s_setprio 0
	s_setprio 1
	v_mfma_f32_16x16x32_bf16 v[54:57], v[146:149], v[162:165], v[54:57]
	v_mfma_f32_16x16x32_bf16 v[50:53], v[154:157], v[162:165], v[50:53]
	v_mfma_f32_16x16x32_bf16 v[38:41], v[146:149], v[178:181], v[38:41]
	v_mfma_f32_16x16x32_bf16 v[34:37], v[154:157], v[178:181], v[34:37]
	v_mfma_f32_16x16x32_bf16 v[22:25], v[146:149], v[186:189], v[22:25]
	v_mfma_f32_16x16x32_bf16 v[18:21], v[154:157], v[186:189], v[18:21]
	v_mfma_f32_16x16x32_bf16 v[6:9], v[146:149], v[194:197], v[6:9]
	v_mfma_f32_16x16x32_bf16 v[2:5], v[154:157], v[194:197], v[2:5]
	v_mfma_f32_16x16x32_bf16 v[54:57], v[150:153], v[166:169], v[54:57]
	v_mfma_f32_16x16x32_bf16 v[50:53], v[158:161], v[166:169], v[50:53]
	v_mfma_f32_16x16x32_bf16 v[38:41], v[150:153], v[182:185], v[38:41]
	v_mfma_f32_16x16x32_bf16 v[34:37], v[158:161], v[182:185], v[34:37]
	v_mfma_f32_16x16x32_bf16 v[22:25], v[150:153], v[190:193], v[22:25]
	v_mfma_f32_16x16x32_bf16 v[18:21], v[158:161], v[190:193], v[18:21]
	v_mfma_f32_16x16x32_bf16 v[6:9], v[150:153], v[198:201], v[6:9]
	v_mfma_f32_16x16x32_bf16 v[2:5], v[158:161], v[198:201], v[2:5]
	s_setprio 0
	s_barrier
	s_add_i32 s60, s60, 2
	s_add_u32 s56, s56, 0x100
	s_addc_u32 s57, s57, 0
	s_add_u32 s2, s2, 0x100
	s_addc_u32 s3, s3, 0
	s_cmp_gt_u32 s60, 13
	.p2alignl 6, 3212836864

; #define PG8_STAGE(bufoff, gbase, voff) do { const char* _gb = (const char*)(gbase); asm volatile("" : "+s"(_gb)); _Pragma("unroll") for (int _i = 0; _i < 2; ++_i) { \
;         unsigned _vo = (voff)[_i]; asm volatile("" : "+v"(_vo));     \
;         __builtin_amdgcn_global_load_lds((const unsigned*)(_gb + _vo), (LAS unsigned*)(lds + (bufoff) + ldsw + _i * 8192), 16, 0, 0); } } while (0)
; #define PG8_LDA(dst, b, h) do { _Pragma("unroll") for (int m = 0; m < 4; ++m) _Pragma("unroll") for (int k = 0; k < 2; ++k) dst[m][k] = *(const LAS bf16x8*)(lds + PG8_SA(b, h) + aoff + m * 2048 + k * 1024); } while (0)
; #define PG8_LDB(dst, b, h) do { _Pragma("unroll") for (int n = 0; n < 2; ++n) _Pragma("unroll") for (int k = 0; k < 2; ++k) dst[n][k] = *(const LAS bf16x8*)(lds + PG8_SB(b, h) + boff + n * 2048 + k * 1024); } while (0)
; #define PG8_MMA(ai, bj, At, Bt) do { __builtin_amdgcn_s_setprio(1); _Pragma("unroll") for (int m = 0; m < 4; ++m) _Pragma("unroll") for (int n = 0; n < 2; ++n) _Pragma("unroll") for (int k = 0; k < 2; ++k) \
;         acc[ai][bj][m][n] = __builtin_amdgcn_mfma_f32_16x16x32_bf16(Bt[n][k], At[m][k], acc[ai][bj][m][n], 0, 0, 0); __builtin_amdgcn_s_setprio(0); } while (0)
; #define PG8_WAIT_V(n) asm volatile("s_waitcnt vmcnt(" #n ")" ::: "memory")
; #define PG8_WAIT_L(n) asm volatile("s_waitcnt lgkmcnt(" #n ")" ::: "memory")
; #define PG8_BAR __builtin_amdgcn_s_barrier()
; #define PG8_SCHED __builtin_amdgcn_sched_barrier(0)
; template <class Epi, class Sched>
; DI void gemm_phase(int wv, LAS unsigned char* lds, const Gemm g, const Sched& S, const Epi& E) {
;     ...
;         for (int t = 0; t < nt; t += 2) {
;             const bool last = (t == nt - 2);
;             const char* a1 = cA + (size_t)(t + 1) * kstep;
;             const char* a2 = last ? nA : cA + (size_t)(t + 2) * kstep; const char* b2 = last ? nB : cB + (size_t)(t + 2) * kstep;
;             const char* a3 = a2 + kstep; const char* b3 = b2 + kstep;
;             PG8_LDB(B0, 0, 0); PG8_LDB(B1, 0, 1); PG8_SCHED; PG8_LDA(At, 0, 0); PG8_STAGE(PG8_SA(1, 1), a1 + hstepA, voffA);
;             PG8_WAIT_V(8); PG8_WAIT_L(0); PG8_BAR; PG8_MMA(0, 0, At, B0); PG8_MMA(0, 1, At, B1); PG8_BAR; PG8_SCHED;
;             PG8_LDA(At, 0, 1); PG8_STAGE(PG8_SB(0, 0), b2, voffB); PG8_STAGE(PG8_SB(0, 1), b2 + hstepB, voffB); PG8_STAGE(PG8_SA(0, 0), a2, voffA);
.LBB0_1886:
	s_ashr_i32 s23, s22, 31
	s_lshl_b64 s[28:29], s[22:23], 19
	s_add_u32 s28, s46, s28
	s_addc_u32 s29, s47, s29
	s_and_b64 s[30:31], s[26:27], exec
	s_cselect_b32 s1, s29, s7
	s_cselect_b32 s3, s28, s6
	s_ashr_i32 s25, s24, 31
	s_lshl_b64 s[30:31], s[24:25], 19
	s_add_u32 s30, s50, s30
	s_addc_u32 s31, s51, s31
	s_and_b64 s[34:35], s[26:27], exec
	s_cselect_b32 s23, s31, s5
	s_cselect_b32 s25, s30, s4
	s_add_u32 s38, s4, 0x100
	s_addc_u32 s39, s5, 0
	s_add_u32 s4, s6, 0x40080
	s_addc_u32 s5, s7, 0
	s_mov_b32 s44, -2
	s_waitcnt vmcnt(0)
	s_add_u32 s6, s4, 0xfffc0080
	s_addc_u32 s7, s5, -1
	s_cmp_eq_u32 s44, 12
	s_cselect_b32 s36, s3, s6
	s_cselect_b32 s37, s1, s7
	s_cselect_b32 s34, s25, s38
	s_cselect_b32 s35, s23, s39
	s_add_u32 s6, s36, 0x80
	s_addc_u32 s7, s37, 0
	s_add_i32 s45, 0, 0x10000
	v_add_u32_e32 v0, s45, v176
	s_add_i32 s70, 0, 0x14000
	ds_read_b128 v[130:133], v0
	ds_read_b128 v[134:137], v0 offset:1024
	ds_read_b128 v[138:141], v0 offset:2048
	ds_read_b128 v[142:145], v0 offset:3072
	v_add_u32_e32 v0, s70, v176
	ds_read_b128 v[146:149], v0
	ds_read_b128 v[150:153], v0 offset:1024
	ds_read_b128 v[154:157], v0 offset:2048
	ds_read_b128 v[158:161], v0 offset:3072
	s_mov_b64 s[48:49], s[4:5]
	v_mov_b32_e32 v0, v172
	ds_read_b128 v[162:165], v177
	ds_read_b128 v[166:169], v177 offset:1024
	ds_read_b128 v[178:181], v177 offset:2048
	ds_read_b128 v[182:185], v177 offset:3072
	ds_read_b128 v[186:189], v177 offset:4096
	ds_read_b128 v[190:193], v177 offset:5120
	ds_read_b128 v[194:197], v177 offset:6144
	ds_read_b128 v[198:201], v177 offset:7168
	s_add_i32 m0, s55, 0xc000
	s_nop 0
	global_load_lds_dwordx4 v0, s[48:49]
	v_mov_b32_e32 v0, v174
	s_add_i32 m0, s55, 0xe000
	s_nop 0
	global_load_lds_dwordx4 v0, s[48:49]
	s_waitcnt vmcnt(8)
	s_waitcnt lgkmcnt(0)
	s_barrier
	s_setprio 1
	s_waitcnt lgkmcnt(0)
	v_mfma_f32_16x16x32_bf16 v[126:129], v[130:133], v[162:165], 0
	v_mfma_f32_16x16x32_bf16 v[122:125], v[138:141], v[162:165], 0
	v_mfma_f32_16x16x32_bf16 v[110:113], v[130:133], v[178:181], 0
	v_mfma_f32_16x16x32_bf16 v[106:109], v[138:141], v[178:181], 0
	v_mfma_f32_16x16x32_bf16 v[94:97], v[130:133], v[186:189], 0
	v_mfma_f32_16x16x32_bf16 v[90:93], v[138:141], v[186:189], 0
	v_mfma_f32_16x16x32_bf16 v[78:81], v[130:133], v[194:197], 0
	v_mfma_f32_16x16x32_bf16 v[74:77], v[138:141], v[194:197], 0
	v_mfma_f32_16x16x32_bf16 v[126:129], v[134:137], v[166:169], v[126:129]
	v_mfma_f32_16x16x32_bf16 v[122:125], v[142:145], v[166:169], v[122:125]
	v_mfma_f32_16x16x32_bf16 v[110:113], v[134:137], v[182:185], v[110:113]
	v_mfma_f32_16x16x32_bf16 v[106:109], v[142:145], v[182:185], v[106:109]
	v_mfma_f32_16x16x32_bf16 v[94:97], v[134:137], v[190:193], v[94:97]
	v_mfma_f32_16x16x32_bf16 v[90:93], v[142:145], v[190:193], v[90:93]
	v_mfma_f32_16x16x32_bf16 v[78:81], v[134:137], v[198:201], v[78:81]
	v_mfma_f32_16x16x32_bf16 v[74:77], v[142:145], v[198:201], v[74:77]
	s_setprio 0
	s_setprio 1
	v_mfma_f32_16x16x32_bf16 v[118:121], v[146:149], v[162:165], 0
	v_mfma_f32_16x16x32_bf16 v[114:117], v[154:157], v[162:165], 0
	v_mfma_f32_16x16x32_bf16 v[102:105], v[146:149], v[178:181], 0
	v_mfma_f32_16x16x32_bf16 v[98:101], v[154:157], v[178:181], 0
	v_mfma_f32_16x16x32_bf16 v[86:89], v[146:149], v[186:189], 0
	v_mfma_f32_16x16x32_bf16 v[82:85], v[154:157], v[186:189], 0
	v_mfma_f32_16x16x32_bf16 v[70:73], v[146:149], v[194:197], 0
	v_mfma_f32_16x16x32_bf16 v[66:69], v[154:157], v[194:197], 0
	v_mfma_f32_16x16x32_bf16 v[118:121], v[150:153], v[166:169], v[118:121]
	v_mfma_f32_16x16x32_bf16 v[114:117], v[158:161], v[166:169], v[114:117]
	v_mfma_f32_16x16x32_bf16 v[102:105], v[150:153], v[182:185], v[102:105]
	v_mfma_f32_16x16x32_bf16 v[98:101], v[158:161], v[182:185], v[98:101]
	v_mfma_f32_16x16x32_bf16 v[86:89], v[150:153], v[190:193], v[86:89]
	v_mfma_f32_16x16x32_bf16 v[82:85], v[158:161], v[190:193], v[82:85]
	v_mfma_f32_16x16x32_bf16 v[70:73], v[150:153], v[198:201], v[70:73]
	v_mfma_f32_16x16x32_bf16 v[66:69], v[158:161], v[198:201], v[66:69]
	s_setprio 0
	s_barrier
	s_mov_b64 s[48:49], s[34:35]
	v_mov_b32_e32 v0, v173
	s_add_i32 s45, s45, s54
	ds_read_b128 v[162:165], v177 offset:16384
	ds_read_b128 v[166:169], v177 offset:17408
	ds_read_b128 v[178:181], v177 offset:18432
	ds_read_b128 v[182:185], v177 offset:19456
	ds_read_b128 v[186:189], v177 offset:20480
	ds_read_b128 v[190:193], v177 offset:21504
	ds_read_b128 v[194:197], v177 offset:22528
	ds_read_b128 v[198:201], v177 offset:23552
	s_mov_b32 m0, s45
	s_nop 0
	global_load_lds_dwordx4 v0, s[48:49]
	v_mov_b32_e32 v0, v175
	s_add_i32 m0, s45, 0x2000
	s_nop 0
	global_load_lds_dwordx4 v0, s[48:49]
	s_add_u32 s48, s34, 0x40000
	s_addc_u32 s49, s35, 0
	v_mov_b32_e32 v0, v173
	s_add_i32 s45, s70, s54
	s_mov_b32 m0, s45
	s_nop 0
	global_load_lds_dwordx4 v0, s[48:49]
	v_mov_b32_e32 v0, v175
	s_add_i32 m0, s45, 0x2000
	s_nop 0
	global_load_lds_dwordx4 v0, s[48:49]
	s_mov_b64 s[48:49], s[36:37]
	v_mov_b32_e32 v0, v172
	s_mov_b32 m0, s55
	s_nop 0
	global_load_lds_dwordx4 v0, s[48:49]
	v_mov_b32_e32 v0, v174
	s_mov_b32 m0, s56
	s_nop 0
	global_load_lds_dwordx4 v0, s[48:49]
	s_waitcnt vmcnt(8)
	s_waitcnt lgkmcnt(0)
	s_barrier
; #define PG8_STAGE(bufoff, gbase, voff) do { const char* _gb = (const char*)(gbase); asm volatile("" : "+s"(_gb)); _Pragma("unroll") for (int _i = 0; _i < 2; ++_i) { \
;         unsigned _vo = (voff)[_i]; asm volatile("" : "+v"(_vo));     \
;         __builtin_amdgcn_global_load_lds((const unsigned*)(_gb + _vo), (LAS unsigned*)(lds + (bufoff) + ldsw + _i * 8192), 16, 0, 0); } } while (0)
; #define PG8_LDA(dst, b, h) do { _Pragma("unroll") for (int m = 0; m < 4; ++m) _Pragma("unroll") for (int k = 0; k < 2; ++k) dst[m][k] = *(const LAS bf16x8*)(lds + PG8_SA(b, h) + aoff + m * 2048 + k * 1024); } while (0)
; #define PG8_LDB(dst, b, h) do { _Pragma("unroll") for (int n = 0; n < 2; ++n) _Pragma("unroll") for (int k = 0; k < 2; ++k) dst[n][k] = *(const LAS bf16x8*)(lds + PG8_SB(b, h) + boff + n * 2048 + k * 1024); } while (0)
; #define PG8_MMA(ai, bj, At, Bt) do { __builtin_amdgcn_s_setprio(1); _Pragma("unroll") for (int m = 0; m < 4; ++m) _Pragma("unroll") for (int n = 0; n < 2; ++n) _Pragma("unroll") for (int k = 0; k < 2; ++k) \
;         acc[ai][bj][m][n] = __builtin_amdgcn_mfma_f32_16x16x32_bf16(Bt[n][k], At[m][k], acc[ai][bj][m][n], 0, 0, 0); __builtin_amdgcn_s_setprio(0); } while (0)
; #define PG8_WAIT_V(n) asm volatile("s_waitcnt vmcnt(" #n ")" ::: "memory")
; #define PG8_WAIT_L(n) asm volatile("s_waitcnt lgkmcnt(" #n ")" ::: "memory")
; #define PG8_BAR __builtin_amdgcn_s_barrier()
; #define PG8_SCHED __builtin_amdgcn_sched_barrier(0)
; template <class Epi, class Sched>
; DI void gemm_phase(int wv, LAS unsigned char* lds, const Gemm g, const Sched& S, const Epi& E) {
;     ...
;             PG8_WAIT_V(8); PG8_WAIT_L(0); PG8_BAR; PG8_MMA(1, 0, At, B0); PG8_MMA(1, 1, At, B1); PG8_BAR; PG8_SCHED;
;             PG8_LDB(B0, 1, 0); PG8_LDB(B1, 1, 1); PG8_SCHED; PG8_LDA(At, 1, 0); PG8_STAGE(PG8_SA(0, 1), a2 + hstepA, voffA);
;             PG8_WAIT_V(8); PG8_WAIT_L(0); PG8_BAR; PG8_MMA(0, 0, At, B0); PG8_MMA(0, 1, At, B1); PG8_BAR; PG8_SCHED;
	s_setprio 1
	s_waitcnt lgkmcnt(0)
	v_mfma_f32_16x16x32_bf16 v[62:65], v[130:133], v[162:165], 0
	v_mfma_f32_16x16x32_bf16 v[58:61], v[138:141], v[162:165], 0
	v_mfma_f32_16x16x32_bf16 v[46:49], v[130:133], v[178:181], 0
	v_mfma_f32_16x16x32_bf16 v[42:45], v[138:141], v[178:181], 0
	v_mfma_f32_16x16x32_bf16 v[30:33], v[130:133], v[186:189], 0
	v_mfma_f32_16x16x32_bf16 v[26:29], v[138:141], v[186:189], 0
	v_mfma_f32_16x16x32_bf16 v[14:17], v[130:133], v[194:197], 0
	v_mfma_f32_16x16x32_bf16 v[10:13], v[138:141], v[194:197], 0
	v_mfma_f32_16x16x32_bf16 v[62:65], v[134:137], v[166:169], v[62:65]
	v_mfma_f32_16x16x32_bf16 v[58:61], v[142:145], v[166:169], v[58:61]
	v_mfma_f32_16x16x32_bf16 v[46:49], v[134:137], v[182:185], v[46:49]
	v_mfma_f32_16x16x32_bf16 v[42:45], v[142:145], v[182:185], v[42:45]
	v_mfma_f32_16x16x32_bf16 v[30:33], v[134:137], v[190:193], v[30:33]
	v_mfma_f32_16x16x32_bf16 v[26:29], v[142:145], v[190:193], v[26:29]
	v_mfma_f32_16x16x32_bf16 v[14:17], v[134:137], v[198:201], v[14:17]
	v_mfma_f32_16x16x32_bf16 v[10:13], v[142:145], v[198:201], v[10:13]
	s_setprio 0
	s_setprio 1
	v_mfma_f32_16x16x32_bf16 v[54:57], v[146:149], v[162:165], 0
	v_mfma_f32_16x16x32_bf16 v[50:53], v[154:157], v[162:165], 0
	v_mfma_f32_16x16x32_bf16 v[38:41], v[146:149], v[178:181], 0
	v_mfma_f32_16x16x32_bf16 v[34:37], v[154:157], v[178:181], 0
	v_mfma_f32_16x16x32_bf16 v[22:25], v[146:149], v[186:189], 0
	v_mfma_f32_16x16x32_bf16 v[18:21], v[154:157], v[186:189], 0
	v_mfma_f32_16x16x32_bf16 v[6:9], v[146:149], v[194:197], 0
	v_mfma_f32_16x16x32_bf16 v[2:5], v[154:157], v[194:197], 0
	v_mfma_f32_16x16x32_bf16 v[54:57], v[150:153], v[166:169], v[54:57]
	v_mfma_f32_16x16x32_bf16 v[50:53], v[158:161], v[166:169], v[50:53]
	v_mfma_f32_16x16x32_bf16 v[38:41], v[150:153], v[182:185], v[38:41]
	v_mfma_f32_16x16x32_bf16 v[34:37], v[158:161], v[182:185], v[34:37]
	v_mfma_f32_16x16x32_bf16 v[22:25], v[150:153], v[190:193], v[22:25]
	v_mfma_f32_16x16x32_bf16 v[18:21], v[158:161], v[190:193], v[18:21]
	v_mfma_f32_16x16x32_bf16 v[6:9], v[150:153], v[198:201], v[6:9]
	v_mfma_f32_16x16x32_bf16 v[2:5], v[158:161], v[198:201], v[2:5]
	s_setprio 0
	s_barrier
	s_add_i32 s45, 0, 0x18000
	v_add_u32_e32 v0, s45, v176
	s_add_i32 s48, 0, 0x1c000
	ds_read_b128 v[130:133], v0
	ds_read_b128 v[134:137], v0 offset:1024
	ds_read_b128 v[138:141], v0 offset:2048
	ds_read_b128 v[142:145], v0 offset:3072
	v_add_u32_e32 v0, s48, v176
	ds_read_b128 v[146:149], v0
	ds_read_b128 v[150:153], v0 offset:1024
	ds_read_b128 v[154:157], v0 offset:2048
	ds_read_b128 v[158:161], v0 offset:3072
	s_add_u32 s36, s36, 0x40000
	s_addc_u32 s37, s37, 0
	v_mov_b32_e32 v0, v172
	s_mov_b32 m0, s57
	ds_read_b128 v[162:165], v177 offset:32768
	ds_read_b128 v[166:169], v177 offset:33792
	ds_read_b128 v[178:181], v177 offset:34816
	ds_read_b128 v[182:185], v177 offset:35840
	ds_read_b128 v[186:189], v177 offset:36864
	ds_read_b128 v[190:193], v177 offset:37888
	ds_read_b128 v[194:197], v177 offset:38912
	ds_read_b128 v[198:201], v177 offset:39936
	s_nop 0
	global_load_lds_dwordx4 v0, s[36:37]
	v_mov_b32_e32 v0, v174
	s_mov_b32 m0, s60
	s_nop 0
	global_load_lds_dwordx4 v0, s[36:37]
	s_waitcnt vmcnt(8)
	s_waitcnt lgkmcnt(0)
	s_barrier
	s_setprio 1
	s_waitcnt lgkmcnt(0)
	v_mfma_f32_16x16x32_bf16 v[126:129], v[130:133], v[162:165], v[126:129]
	v_mfma_f32_16x16x32_bf16 v[122:125], v[138:141], v[162:165], v[122:125]
	v_mfma_f32_16x16x32_bf16 v[110:113], v[130:133], v[178:181], v[110:113]
	v_mfma_f32_16x16x32_bf16 v[106:109], v[138:141], v[178:181], v[106:109]
	v_mfma_f32_16x16x32_bf16 v[94:97], v[130:133], v[186:189], v[94:97]
	v_mfma_f32_16x16x32_bf16 v[90:93], v[138:141], v[186:189], v[90:93]
	v_mfma_f32_16x16x32_bf16 v[78:81], v[130:133], v[194:197], v[78:81]
	v_mfma_f32_16x16x32_bf16 v[74:77], v[138:141], v[194:197], v[74:77]
	v_mfma_f32_16x16x32_bf16 v[126:129], v[134:137], v[166:169], v[126:129]
	v_mfma_f32_16x16x32_bf16 v[122:125], v[142:145], v[166:169], v[122:125]
	v_mfma_f32_16x16x32_bf16 v[110:113], v[134:137], v[182:185], v[110:113]
	v_mfma_f32_16x16x32_bf16 v[106:109], v[142:145], v[182:185], v[106:109]
	v_mfma_f32_16x16x32_bf16 v[94:97], v[134:137], v[190:193], v[94:97]
	v_mfma_f32_16x16x32_bf16 v[90:93], v[142:145], v[190:193], v[90:93]
	v_mfma_f32_16x16x32_bf16 v[78:81], v[134:137], v[198:201], v[78:81]
	v_mfma_f32_16x16x32_bf16 v[74:77], v[142:145], v[198:201], v[74:77]
	s_setprio 0
	s_setprio 1
	v_mfma_f32_16x16x32_bf16 v[118:121], v[146:149], v[162:165], v[118:121]
	v_mfma_f32_16x16x32_bf16 v[114:117], v[154:157], v[162:165], v[114:117]
	v_mfma_f32_16x16x32_bf16 v[102:105], v[146:149], v[178:181], v[102:105]
	v_mfma_f32_16x16x32_bf16 v[98:101], v[154:157], v[178:181], v[98:101]
	v_mfma_f32_16x16x32_bf16 v[86:89], v[146:149], v[186:189], v[86:89]
	v_mfma_f32_16x16x32_bf16 v[82:85], v[154:157], v[186:189], v[82:85]
	v_mfma_f32_16x16x32_bf16 v[70:73], v[146:149], v[194:197], v[70:73]
	v_mfma_f32_16x16x32_bf16 v[66:69], v[154:157], v[194:197], v[66:69]
	v_mfma_f32_16x16x32_bf16 v[118:121], v[150:153], v[166:169], v[118:121]
	v_mfma_f32_16x16x32_bf16 v[114:117], v[158:161], v[166:169], v[114:117]
	v_mfma_f32_16x16x32_bf16 v[102:105], v[150:153], v[182:185], v[102:105]
	v_mfma_f32_16x16x32_bf16 v[98:101], v[158:161], v[182:185], v[98:101]
	v_mfma_f32_16x16x32_bf16 v[86:89], v[150:153], v[190:193], v[86:89]
	v_mfma_f32_16x16x32_bf16 v[82:85], v[158:161], v[190:193], v[82:85]
	v_mfma_f32_16x16x32_bf16 v[70:73], v[150:153], v[198:201], v[70:73]
	v_mfma_f32_16x16x32_bf16 v[66:69], v[158:161], v[198:201], v[66:69]
	s_setprio 0
	s_barrier
; #define PG8_STAGE(bufoff, gbase, voff) do { const char* _gb = (const char*)(gbase); asm volatile("" : "+s"(_gb)); _Pragma("unroll") for (int _i = 0; _i < 2; ++_i) { \
;         unsigned _vo = (voff)[_i]; asm volatile("" : "+v"(_vo));     \
;         __builtin_amdgcn_global_load_lds((const unsigned*)(_gb + _vo), (LAS unsigned*)(lds + (bufoff) + ldsw + _i * 8192), 16, 0, 0); } } while (0)
; #define PG8_LDA(dst, b, h) do { _Pragma("unroll") for (int m = 0; m < 4; ++m) _Pragma("unroll") for (int k = 0; k < 2; ++k) dst[m][k] = *(const LAS bf16x8*)(lds + PG8_SA(b, h) + aoff + m * 2048 + k * 1024); } while (0)
; #define PG8_MMA(ai, bj, At, Bt) do { __builtin_amdgcn_s_setprio(1); _Pragma("unroll") for (int m = 0; m < 4; ++m) _Pragma("unroll") for (int n = 0; n < 2; ++n) _Pragma("unroll") for (int k = 0; k < 2; ++k) \
;         acc[ai][bj][m][n] = __builtin_amdgcn_mfma_f32_16x16x32_bf16(Bt[n][k], At[m][k], acc[ai][bj][m][n], 0, 0, 0); __builtin_amdgcn_s_setprio(0); } while (0)
; #define PG8_WAIT_V(n) asm volatile("s_waitcnt vmcnt(" #n ")" ::: "memory")
; #define PG8_WAIT_L(n) asm volatile("s_waitcnt lgkmcnt(" #n ")" ::: "memory")
; #define PG8_BAR __builtin_amdgcn_s_barrier()
; #define PG8_SCHED __builtin_amdgcn_sched_barrier(0)
; template <class Epi, class Sched>
; DI void gemm_phase(int wv, LAS unsigned char* lds, const Gemm g, const Sched& S, const Epi& E) {
;     ...
;             PG8_LDA(At, 1, 1); PG8_STAGE(PG8_SB(1, 0), b3, voffB); PG8_STAGE(PG8_SB(1, 1), b3 + hstepB, voffB); PG8_STAGE(PG8_SA(1, 0), a3, voffA);
;             PG8_WAIT_V(8); PG8_WAIT_L(0); PG8_BAR; PG8_MMA(1, 0, At, B0); PG8_MMA(1, 1, At, B1); PG8_BAR; PG8_SCHED;
;         }
	s_add_u32 s36, s34, 0x80
	s_addc_u32 s37, s35, 0
	v_mov_b32_e32 v0, v173
	s_add_i32 s45, s45, s54
	ds_read_b128 v[162:165], v177 offset:49152
	ds_read_b128 v[166:169], v177 offset:50176
	ds_read_b128 v[178:181], v177 offset:51200
	ds_read_b128 v[182:185], v177 offset:52224
	ds_read_b128 v[186:189], v177 offset:53248
	ds_read_b128 v[190:193], v177 offset:54272
	ds_read_b128 v[194:197], v177 offset:55296
	ds_read_b128 v[198:201], v177 offset:56320
	s_mov_b32 m0, s45
	s_nop 0
	global_load_lds_dwordx4 v0, s[36:37]
	v_mov_b32_e32 v0, v175
	s_add_i32 m0, s45, 0x2000
	s_add_u32 s34, s34, 0x40080
	global_load_lds_dwordx4 v0, s[36:37]
	s_addc_u32 s35, s35, 0
	v_mov_b32_e32 v0, v173
	s_add_i32 s36, s48, s54
	s_mov_b32 m0, s36
	s_nop 0
	global_load_lds_dwordx4 v0, s[34:35]
	v_mov_b32_e32 v0, v175
	s_add_i32 m0, s36, 0x2000
	s_nop 0
	global_load_lds_dwordx4 v0, s[34:35]
	v_mov_b32_e32 v0, v172
	s_mov_b32 m0, s67
	s_nop 0
	global_load_lds_dwordx4 v0, s[6:7]
	v_mov_b32_e32 v0, v174
	s_mov_b32 m0, s69
	s_nop 0
	global_load_lds_dwordx4 v0, s[6:7]
	s_waitcnt vmcnt(8)
	s_waitcnt lgkmcnt(0)
	s_barrier
	s_setprio 1
	s_waitcnt lgkmcnt(0)
	v_mfma_f32_16x16x32_bf16 v[62:65], v[130:133], v[162:165], v[62:65]
	v_mfma_f32_16x16x32_bf16 v[58:61], v[138:141], v[162:165], v[58:61]
	v_mfma_f32_16x16x32_bf16 v[46:49], v[130:133], v[178:181], v[46:49]
	v_mfma_f32_16x16x32_bf16 v[42:45], v[138:141], v[178:181], v[42:45]
	v_mfma_f32_16x16x32_bf16 v[30:33], v[130:133], v[186:189], v[30:33]
	v_mfma_f32_16x16x32_bf16 v[26:29], v[138:141], v[186:189], v[26:29]
	v_mfma_f32_16x16x32_bf16 v[14:17], v[130:133], v[194:197], v[14:17]
	v_mfma_f32_16x16x32_bf16 v[10:13], v[138:141], v[194:197], v[10:13]
	v_mfma_f32_16x16x32_bf16 v[62:65], v[134:137], v[166:169], v[62:65]
	v_mfma_f32_16x16x32_bf16 v[58:61], v[142:145], v[166:169], v[58:61]
	v_mfma_f32_16x16x32_bf16 v[46:49], v[134:137], v[182:185], v[46:49]
	v_mfma_f32_16x16x32_bf16 v[42:45], v[142:145], v[182:185], v[42:45]
	v_mfma_f32_16x16x32_bf16 v[30:33], v[134:137], v[190:193], v[30:33]
	v_mfma_f32_16x16x32_bf16 v[26:29], v[142:145], v[190:193], v[26:29]
	v_mfma_f32_16x16x32_bf16 v[14:17], v[134:137], v[198:201], v[14:17]
	v_mfma_f32_16x16x32_bf16 v[10:13], v[142:145], v[198:201], v[10:13]
	s_setprio 0
	s_setprio 1
	v_mfma_f32_16x16x32_bf16 v[54:57], v[146:149], v[162:165], v[54:57]
	v_mfma_f32_16x16x32_bf16 v[50:53], v[154:157], v[162:165], v[50:53]
	v_mfma_f32_16x16x32_bf16 v[38:41], v[146:149], v[178:181], v[38:41]
	v_mfma_f32_16x16x32_bf16 v[34:37], v[154:157], v[178:181], v[34:37]
	v_mfma_f32_16x16x32_bf16 v[22:25], v[146:149], v[186:189], v[22:25]
	v_mfma_f32_16x16x32_bf16 v[18:21], v[154:157], v[186:189], v[18:21]
	v_mfma_f32_16x16x32_bf16 v[6:9], v[146:149], v[194:197], v[6:9]
	v_mfma_f32_16x16x32_bf16 v[2:5], v[154:157], v[194:197], v[2:5]
	v_mfma_f32_16x16x32_bf16 v[54:57], v[150:153], v[166:169], v[54:57]
	v_mfma_f32_16x16x32_bf16 v[50:53], v[158:161], v[166:169], v[50:53]
	v_mfma_f32_16x16x32_bf16 v[38:41], v[150:153], v[182:185], v[38:41]
	v_mfma_f32_16x16x32_bf16 v[34:37], v[158:161], v[182:185], v[34:37]
	v_mfma_f32_16x16x32_bf16 v[22:25], v[150:153], v[190:193], v[22:25]
	v_mfma_f32_16x16x32_bf16 v[18:21], v[158:161], v[190:193], v[18:21]
	v_mfma_f32_16x16x32_bf16 v[6:9], v[150:153], v[198:201], v[6:9]
	v_mfma_f32_16x16x32_bf16 v[2:5], v[158:161], v[198:201], v[2:5]
	s_setprio 0
	s_barrier
	s_add_i32 s44, s44, 2
	s_add_u32 s38, s38, 0x100
	s_addc_u32 s39, s39, 0
	s_add_u32 s4, s4, 0x100
	s_addc_u32 s5, s5, 0
	s_cmp_gt_u32 s44, 13
	.p2alignl 6, 3212836864

; template <class Epi, class Sched>
; DI void gemm_phase(int wv, LAS unsigned char* lds, const Gemm g, const Sched& S, const Epi& E) {
;     ...
;         const bool has_next = S.next(ui + 1, nxt);
;         const char* nA = has_next ? (const char*)g.A + (size_t)nxt.pm * tstepA : cA; const char* nB = has_next ? (const char*)g.Bt + (size_t)nxt.pn * tstepB : cB;
;     ...
; #pragma unroll
;         for (int a = 0; a < 2; ++a)
; #pragma unroll
;             for (int b = 0; b < 2; ++b)
; #pragma unroll
;                 for (int m = 0; m < 4; ++m)
; #pragma unroll
;                     for (int n = 0; n < 2; ++n) acc[a][b][m][n] = (f32x4){0.f, 0.f, 0.f, 0.f};
.LBB0_2084:
	s_ashr_i32 s19, s18, 31
	s_lshl_b64 s[0:1], s[18:19], 19
	s_add_u32 s20, s36, s0
	s_addc_u32 s21, s37, s1
	s_and_b64 s[0:1], s[14:15], exec
	s_cselect_b32 s0, s21, s29
	s_cselect_b32 s1, s20, s28
	s_ashr_i32 s17, s16, 31
	s_lshl_b64 s[22:23], s[16:17], 19
	s_add_u32 s22, s46, s22
	s_addc_u32 s23, s47, s23
	s_and_b64 s[30:31], s[14:15], exec
	s_cselect_b32 s3, s23, s27
	s_cselect_b32 s17, s22, s26
	s_add_u32 s19, s26, 0x100
	s_addc_u32 s25, s27, 0
	s_add_u32 s26, s28, 0x40080
	v_mov_b32_e32 v2, 0
	s_addc_u32 s27, s29, 0
	s_mov_b32 s56, -2
	v_mov_b32_e32 v3, v2
	v_mov_b32_e32 v4, v2
	v_mov_b32_e32 v5, v2
	v_mov_b32_e32 v6, v2
	v_mov_b32_e32 v7, v2
	v_mov_b32_e32 v8, v2
	v_mov_b32_e32 v9, v2
	v_mov_b32_e32 v10, v2
	v_mov_b32_e32 v11, v2
	v_mov_b32_e32 v12, v2
	v_mov_b32_e32 v13, v2
	v_mov_b32_e32 v14, v2
	v_mov_b32_e32 v15, v2
	v_mov_b32_e32 v16, v2
	v_mov_b32_e32 v17, v2
	v_mov_b32_e32 v18, v2
	v_mov_b32_e32 v19, v2
	v_mov_b32_e32 v20, v2
	v_mov_b32_e32 v21, v2
	v_mov_b32_e32 v22, v2
	v_mov_b32_e32 v23, v2
	v_mov_b32_e32 v24, v2
	v_mov_b32_e32 v25, v2
	v_mov_b32_e32 v26, v2
	v_mov_b32_e32 v27, v2
	v_mov_b32_e32 v28, v2
	v_mov_b32_e32 v29, v2
	v_mov_b32_e32 v30, v2
	v_mov_b32_e32 v31, v2
	v_mov_b32_e32 v32, v2
	v_mov_b32_e32 v33, v2
	v_mov_b32_e32 v66, v2
	v_mov_b32_e32 v67, v2
	v_mov_b32_e32 v68, v2
	v_mov_b32_e32 v69, v2
	v_mov_b32_e32 v70, v2
	v_mov_b32_e32 v71, v2
	v_mov_b32_e32 v72, v2
	v_mov_b32_e32 v73, v2
	v_mov_b32_e32 v74, v2
	v_mov_b32_e32 v75, v2
	v_mov_b32_e32 v76, v2
	v_mov_b32_e32 v77, v2
	v_mov_b32_e32 v78, v2
	v_mov_b32_e32 v79, v2
	v_mov_b32_e32 v80, v2
	v_mov_b32_e32 v81, v2
	s_waitcnt vmcnt(0)
	v_mov_b32_e32 v82, v2
	v_mov_b32_e32 v83, v2
	v_mov_b32_e32 v84, v2
	v_mov_b32_e32 v85, v2
	v_mov_b32_e32 v86, v2
	v_mov_b32_e32 v87, v2
	v_mov_b32_e32 v88, v2
	v_mov_b32_e32 v89, v2
	v_mov_b32_e32 v90, v2
	v_mov_b32_e32 v91, v2
	v_mov_b32_e32 v92, v2
	v_mov_b32_e32 v93, v2
	v_mov_b32_e32 v94, v2
	v_mov_b32_e32 v95, v2
	v_mov_b32_e32 v96, v2
	v_mov_b32_e32 v97, v2
	v_mov_b32_e32 v34, v2
	v_mov_b32_e32 v35, v2
	v_mov_b32_e32 v36, v2
	v_mov_b32_e32 v37, v2
	v_mov_b32_e32 v38, v2
	v_mov_b32_e32 v39, v2
	v_mov_b32_e32 v40, v2
	v_mov_b32_e32 v41, v2
	v_mov_b32_e32 v42, v2
	v_mov_b32_e32 v43, v2
	v_mov_b32_e32 v44, v2
	v_mov_b32_e32 v45, v2
	v_mov_b32_e32 v46, v2
	v_mov_b32_e32 v47, v2
	v_mov_b32_e32 v48, v2
	v_mov_b32_e32 v49, v2
	v_mov_b32_e32 v50, v2
	v_mov_b32_e32 v51, v2
	v_mov_b32_e32 v52, v2
	v_mov_b32_e32 v53, v2
	v_mov_b32_e32 v54, v2
	v_mov_b32_e32 v55, v2
	v_mov_b32_e32 v56, v2
	v_mov_b32_e32 v57, v2
	v_mov_b32_e32 v58, v2
	v_mov_b32_e32 v59, v2
	v_mov_b32_e32 v60, v2
	v_mov_b32_e32 v61, v2
	v_mov_b32_e32 v62, v2
	v_mov_b32_e32 v63, v2
	v_mov_b32_e32 v64, v2
	v_mov_b32_e32 v65, v2
	v_mov_b32_e32 v98, v2
	v_mov_b32_e32 v99, v2
	v_mov_b32_e32 v100, v2
	v_mov_b32_e32 v101, v2
	v_mov_b32_e32 v102, v2
	v_mov_b32_e32 v103, v2
	v_mov_b32_e32 v104, v2
	v_mov_b32_e32 v105, v2
	v_mov_b32_e32 v106, v2
	v_mov_b32_e32 v107, v2
	v_mov_b32_e32 v108, v2
	v_mov_b32_e32 v109, v2
	v_mov_b32_e32 v110, v2
	v_mov_b32_e32 v111, v2
	v_mov_b32_e32 v112, v2
	v_mov_b32_e32 v113, v2
	v_mov_b32_e32 v114, v2
	v_mov_b32_e32 v115, v2
	v_mov_b32_e32 v116, v2
	v_mov_b32_e32 v117, v2
	v_mov_b32_e32 v118, v2
	v_mov_b32_e32 v119, v2
	v_mov_b32_e32 v120, v2
	v_mov_b32_e32 v121, v2
	v_mov_b32_e32 v122, v2
	v_mov_b32_e32 v123, v2
	v_mov_b32_e32 v124, v2
	v_mov_b32_e32 v125, v2
	v_mov_b32_e32 v126, v2
	v_mov_b32_e32 v127, v2
	v_mov_b32_e32 v128, v2
	v_mov_b32_e32 v129, v2
	.p2alignl 6, 3212836864

; DI f32x16 zero16() { f32x16 z; for (int i = 0; i < 16; ++i) z[i] = 0.f; return z; }
; DI void nsa_attn_phase(int wv, LAS unsigned char* lds, const bf16_t* Q, const bf16_t* slab, const bf16_t* VT2, const float* gates, const bf16_t* KCMP, const bf16_t* VCMPT,
;                        const float* rel_bias, bf16_t* O) {
;     ...
;                 float m = 0.f, l = 0.f; f32x16 o[2] = {zero16(), zero16()};
;     ...
;                 int j = __builtin_ctz(tiles); tiles &= tiles - 1;
;                 gload(j); lstore(0);
;                 int jn = -1; if (tiles) { jn = __builtin_ctz(tiles); tiles &= tiles - 1; gload(jn); }
;                 __syncthreads();
;                 int bi = 0;
.LBB0_2418:
	s_or_b64 exec, exec, s[6:7]
	v_mov_b32_e32 v14, v1
	v_mov_b32_e32 v15, v1
	v_lshl_add_u64 v[220:221], v[2:3], 0, v[0:1]
	v_mov_b32_e32 v0, v1
	v_mov_b32_e32 v2, v1
	v_mov_b32_e32 v3, v1
	v_mov_b32_e32 v4, v1
	v_mov_b32_e32 v5, v1
	v_mov_b32_e32 v6, v1
	v_mov_b32_e32 v7, v1
	v_mov_b32_e32 v8, v1
	v_mov_b32_e32 v9, v1
	v_mov_b32_e32 v10, v1
	v_mov_b32_e32 v11, v1
	v_mov_b32_e32 v12, v1
	v_mov_b32_e32 v13, v1
	v_mov_b64_e32 v[126:127], v[14:15]
	v_mov_b64_e32 v[142:143], v[14:15]
	s_xor_b64 s[12:13], s[8:9], -1
	v_lshl_add_u64 v[218:219], s[4:5], 0, v[214:215]
	s_xor_b64 s[26:27], s[8:9], -1
	s_mov_b32 s0, 0
	s_mov_b64 s[28:29], 0
	v_mov_b64_e32 v[124:125], v[12:13]
	v_mov_b64_e32 v[122:123], v[10:11]
	v_mov_b64_e32 v[120:121], v[8:9]
	v_mov_b64_e32 v[118:119], v[6:7]
	v_mov_b64_e32 v[116:117], v[4:5]
	v_mov_b64_e32 v[114:115], v[2:3]
	v_mov_b64_e32 v[112:113], v[0:1]
	v_mov_b64_e32 v[140:141], v[12:13]
	v_mov_b64_e32 v[138:139], v[10:11]
	v_mov_b64_e32 v[136:137], v[8:9]
	v_mov_b64_e32 v[134:135], v[6:7]
	v_mov_b64_e32 v[132:133], v[4:5]
	v_mov_b64_e32 v[130:131], v[2:3]
	v_mov_b64_e32 v[128:129], v[0:1]
	v_mov_b32_e32 v4, 0
	s_waitcnt lgkmcnt(0)
	s_barrier
	s_branch .LBB0_2421
	.p2alignl 6, 3212836864

; template <class Epi, class Sched>
; DI void gemm_phase(int wv, LAS unsigned char* lds, const Gemm g, const Sched& S, const Epi& E) {
;     ...
;         const bool has_next = S.next(ui + 1, nxt);
;         const char* nA = has_next ? (const char*)g.A + (size_t)nxt.pm * tstepA : cA; const char* nB = has_next ? (const char*)g.Bt + (size_t)nxt.pn * tstepB : cB;
;     ...
; #pragma unroll
;         for (int a = 0; a < 2; ++a)
; #pragma unroll
;             for (int b = 0; b < 2; ++b)
; #pragma unroll
;                 for (int m = 0; m < 4; ++m)
; #pragma unroll
;                     for (int n = 0; n < 2; ++n) acc[a][b][m][n] = (f32x4){0.f, 0.f, 0.f, 0.f};
.LBB0_2497:
	s_ashr_i32 s31, s30, 31
	s_lshl_b64 s[6:7], s[30:31], 19
	s_add_u32 s48, s44, s6
	s_addc_u32 s49, s45, s7
	s_and_b64 s[6:7], s[36:37], exec
	s_cselect_b32 s1, s49, s5
	s_cselect_b32 s31, s48, s4
	s_ashr_i32 s35, s34, 31
	s_lshl_b64 s[6:7], s[34:35], 19
	s_add_u32 s50, s46, s6
	s_addc_u32 s51, s47, s7
	s_and_b64 s[6:7], s[36:37], exec
	s_cselect_b32 s35, s51, s3
	s_cselect_b32 s39, s50, s2
	s_add_u32 s85, s2, 0x100
	s_addc_u32 s90, s3, 0
	s_add_u32 s2, s4, 0x40080
	s_waitcnt lgkmcnt(0)
	v_mov_b32_e32 v2, 0
	s_addc_u32 s3, s5, 0
	s_mov_b32 s91, -2
	v_mov_b32_e32 v3, v2
	v_mov_b32_e32 v4, v2
	v_mov_b32_e32 v5, v2
	v_mov_b32_e32 v6, v2
	v_mov_b32_e32 v7, v2
	v_mov_b32_e32 v8, v2
	v_mov_b32_e32 v9, v2
	v_mov_b32_e32 v18, v2
	v_mov_b32_e32 v19, v2
	v_mov_b32_e32 v20, v2
	v_mov_b32_e32 v21, v2
	v_mov_b32_e32 v22, v2
	v_mov_b32_e32 v23, v2
	v_mov_b32_e32 v24, v2
	v_mov_b32_e32 v25, v2
	v_mov_b32_e32 v34, v2
	v_mov_b32_e32 v35, v2
	v_mov_b32_e32 v36, v2
	v_mov_b32_e32 v37, v2
	v_mov_b32_e32 v38, v2
	v_mov_b32_e32 v39, v2
	v_mov_b32_e32 v40, v2
	v_mov_b32_e32 v41, v2
	v_mov_b32_e32 v50, v2
	v_mov_b32_e32 v51, v2
	v_mov_b32_e32 v52, v2
	v_mov_b32_e32 v53, v2
	v_mov_b32_e32 v54, v2
	v_mov_b32_e32 v55, v2
	v_mov_b32_e32 v56, v2
	v_mov_b32_e32 v57, v2
	v_mov_b32_e32 v10, v2
	v_mov_b32_e32 v11, v2
	v_mov_b32_e32 v12, v2
	v_mov_b32_e32 v13, v2
	v_mov_b32_e32 v14, v2
	v_mov_b32_e32 v15, v2
	v_mov_b32_e32 v16, v2
	v_mov_b32_e32 v17, v2
	v_mov_b32_e32 v26, v2
	v_mov_b32_e32 v27, v2
	v_mov_b32_e32 v28, v2
	v_mov_b32_e32 v29, v2
	v_mov_b32_e32 v30, v2
	v_mov_b32_e32 v31, v2
	v_mov_b32_e32 v32, v2
	v_mov_b32_e32 v33, v2
	v_mov_b32_e32 v42, v2
	v_mov_b32_e32 v43, v2
	v_mov_b32_e32 v44, v2
	v_mov_b32_e32 v45, v2
	v_mov_b32_e32 v46, v2
	v_mov_b32_e32 v47, v2
	v_mov_b32_e32 v48, v2
	v_mov_b32_e32 v49, v2
	v_mov_b32_e32 v58, v2
	v_mov_b32_e32 v59, v2
	v_mov_b32_e32 v60, v2
	v_mov_b32_e32 v61, v2
	v_mov_b32_e32 v62, v2
	v_mov_b32_e32 v63, v2
	v_mov_b32_e32 v64, v2
	v_mov_b32_e32 v65, v2
	v_mov_b32_e32 v66, v2
	v_mov_b32_e32 v67, v2
	v_mov_b32_e32 v68, v2
	v_mov_b32_e32 v69, v2
	v_mov_b32_e32 v70, v2
	v_mov_b32_e32 v71, v2
	v_mov_b32_e32 v72, v2
	v_mov_b32_e32 v73, v2
	s_waitcnt vmcnt(0)
	v_mov_b32_e32 v82, v2
	v_mov_b32_e32 v83, v2
	v_mov_b32_e32 v84, v2
	v_mov_b32_e32 v85, v2
	v_mov_b32_e32 v86, v2
	v_mov_b32_e32 v87, v2
	v_mov_b32_e32 v88, v2
	v_mov_b32_e32 v89, v2
	v_mov_b32_e32 v106, v2
	v_mov_b32_e32 v107, v2
	v_mov_b32_e32 v108, v2
	v_mov_b32_e32 v109, v2
	v_mov_b32_e32 v110, v2
	v_mov_b32_e32 v111, v2
	v_mov_b32_e32 v112, v2
	v_mov_b32_e32 v113, v2
	v_mov_b32_e32 v130, v2
	v_mov_b32_e32 v131, v2
	v_mov_b32_e32 v132, v2
	v_mov_b32_e32 v133, v2
	v_mov_b32_e32 v134, v2
	v_mov_b32_e32 v135, v2
	v_mov_b32_e32 v136, v2
	v_mov_b32_e32 v137, v2
	v_mov_b32_e32 v74, v2
	v_mov_b32_e32 v75, v2
	v_mov_b32_e32 v76, v2
	v_mov_b32_e32 v77, v2
	v_mov_b32_e32 v78, v2
	v_mov_b32_e32 v79, v2
	v_mov_b32_e32 v80, v2
	v_mov_b32_e32 v81, v2
	v_mov_b32_e32 v90, v2
	v_mov_b32_e32 v91, v2
	v_mov_b32_e32 v92, v2
	v_mov_b32_e32 v93, v2
	v_mov_b32_e32 v94, v2
	v_mov_b32_e32 v95, v2
	v_mov_b32_e32 v96, v2
	v_mov_b32_e32 v97, v2
	v_mov_b32_e32 v114, v2
	v_mov_b32_e32 v115, v2
	v_mov_b32_e32 v116, v2
	v_mov_b32_e32 v117, v2
	v_mov_b32_e32 v118, v2
	v_mov_b32_e32 v119, v2
	v_mov_b32_e32 v120, v2
	v_mov_b32_e32 v121, v2
	v_mov_b32_e32 v146, v2
	v_mov_b32_e32 v147, v2
	v_mov_b32_e32 v148, v2
	v_mov_b32_e32 v149, v2
	v_mov_b32_e32 v150, v2
	v_mov_b32_e32 v151, v2
	v_mov_b32_e32 v152, v2
	v_mov_b32_e32 v153, v2
	s_waitcnt vmcnt(0)
	.p2alignl 6, 3212836864

; template <class Epi, class Sched>
; DI void gemm_phase(int wv, LAS unsigned char* lds, const Gemm g, const Sched& S, const Epi& E) {
;     ...
;         const bool has_next = S.next(ui + 1, nxt);
;         const char* nA = has_next ? (const char*)g.A + (size_t)nxt.pm * tstepA : cA; const char* nB = has_next ? (const char*)g.Bt + (size_t)nxt.pn * tstepB : cB;
;     ...
; #pragma unroll
;         for (int a = 0; a < 2; ++a)
; #pragma unroll
;             for (int b = 0; b < 2; ++b)
; #pragma unroll
;                 for (int m = 0; m < 4; ++m)
; #pragma unroll
;                     for (int n = 0; n < 2; ++n) acc[a][b][m][n] = (f32x4){0.f, 0.f, 0.f, 0.f};
.LBB0_2648:
	s_add_u32 s3, s4, 0x100
	s_addc_u32 s56, s5, 0
	s_add_u32 s4, s24, 0x30080
	v_mov_b32_e32 v2, 0
	s_addc_u32 s5, s25, 0
	s_mov_b32 s57, -2
	v_mov_b32_e32 v3, v2
	v_mov_b32_e32 v4, v2
	v_mov_b32_e32 v5, v2
	v_mov_b32_e32 v6, v2
	v_mov_b32_e32 v7, v2
	v_mov_b32_e32 v8, v2
	v_mov_b32_e32 v9, v2
	v_mov_b32_e32 v10, v2
	v_mov_b32_e32 v11, v2
	v_mov_b32_e32 v12, v2
	v_mov_b32_e32 v13, v2
	v_mov_b32_e32 v14, v2
	v_mov_b32_e32 v15, v2
	v_mov_b32_e32 v16, v2
	v_mov_b32_e32 v17, v2
	v_mov_b32_e32 v18, v2
	v_mov_b32_e32 v19, v2
	v_mov_b32_e32 v20, v2
	v_mov_b32_e32 v21, v2
	v_mov_b32_e32 v22, v2
	v_mov_b32_e32 v23, v2
	v_mov_b32_e32 v24, v2
	v_mov_b32_e32 v25, v2
	v_mov_b32_e32 v26, v2
	v_mov_b32_e32 v27, v2
	v_mov_b32_e32 v28, v2
	v_mov_b32_e32 v29, v2
	v_mov_b32_e32 v30, v2
	v_mov_b32_e32 v31, v2
	v_mov_b32_e32 v32, v2
	v_mov_b32_e32 v33, v2
	v_mov_b32_e32 v66, v2
	v_mov_b32_e32 v67, v2
	v_mov_b32_e32 v68, v2
	v_mov_b32_e32 v69, v2
	v_mov_b32_e32 v70, v2
	v_mov_b32_e32 v71, v2
	v_mov_b32_e32 v72, v2
	v_mov_b32_e32 v73, v2
	v_mov_b32_e32 v74, v2
	v_mov_b32_e32 v75, v2
	v_mov_b32_e32 v76, v2
	v_mov_b32_e32 v77, v2
	v_mov_b32_e32 v78, v2
	v_mov_b32_e32 v79, v2
	v_mov_b32_e32 v80, v2
	v_mov_b32_e32 v81, v2
	v_mov_b32_e32 v90, v2
	v_mov_b32_e32 v91, v2
	v_mov_b32_e32 v92, v2
	v_mov_b32_e32 v93, v2
	v_mov_b32_e32 v94, v2
	v_mov_b32_e32 v95, v2
	v_mov_b32_e32 v96, v2
	v_mov_b32_e32 v97, v2
	v_mov_b32_e32 v114, v2
	v_mov_b32_e32 v115, v2
	v_mov_b32_e32 v116, v2
	v_mov_b32_e32 v117, v2
	v_mov_b32_e32 v118, v2
	v_mov_b32_e32 v119, v2
	v_mov_b32_e32 v120, v2
	v_mov_b32_e32 v121, v2
	v_mov_b32_e32 v34, v2
	v_mov_b32_e32 v35, v2
	v_mov_b32_e32 v36, v2
	v_mov_b32_e32 v37, v2
	v_mov_b32_e32 v38, v2
	v_mov_b32_e32 v39, v2
	v_mov_b32_e32 v40, v2
	v_mov_b32_e32 v41, v2
	v_mov_b32_e32 v42, v2
	v_mov_b32_e32 v43, v2
	v_mov_b32_e32 v44, v2
	v_mov_b32_e32 v45, v2
	v_mov_b32_e32 v46, v2
	v_mov_b32_e32 v47, v2
	v_mov_b32_e32 v48, v2
	v_mov_b32_e32 v49, v2
	v_mov_b32_e32 v50, v2
	v_mov_b32_e32 v51, v2
	v_mov_b32_e32 v52, v2
	v_mov_b32_e32 v53, v2
	v_mov_b32_e32 v54, v2
	v_mov_b32_e32 v55, v2
	v_mov_b32_e32 v56, v2
	v_mov_b32_e32 v57, v2
	v_mov_b32_e32 v58, v2
	v_mov_b32_e32 v59, v2
	v_mov_b32_e32 v60, v2
	v_mov_b32_e32 v61, v2
	v_mov_b32_e32 v62, v2
	v_mov_b32_e32 v63, v2
	v_mov_b32_e32 v64, v2
	v_mov_b32_e32 v65, v2
	v_mov_b32_e32 v130, v2
	v_mov_b32_e32 v131, v2
	v_mov_b32_e32 v132, v2
	v_mov_b32_e32 v133, v2
	v_mov_b32_e32 v134, v2
	v_mov_b32_e32 v135, v2
	v_mov_b32_e32 v136, v2
	v_mov_b32_e32 v137, v2
	s_waitcnt vmcnt(0)
	v_mov_b32_e32 v138, v2
	v_mov_b32_e32 v139, v2
	v_mov_b32_e32 v140, v2
	v_mov_b32_e32 v141, v2
	v_mov_b32_e32 v142, v2
	v_mov_b32_e32 v143, v2
	v_mov_b32_e32 v144, v2
	v_mov_b32_e32 v145, v2
	v_mov_b32_e32 v146, v2
	v_mov_b32_e32 v147, v2
	v_mov_b32_e32 v148, v2
	v_mov_b32_e32 v149, v2
	v_mov_b32_e32 v150, v2
	v_mov_b32_e32 v151, v2
	v_mov_b32_e32 v152, v2
	v_mov_b32_e32 v153, v2
	v_mov_b32_e32 v154, v2
	v_mov_b32_e32 v155, v2
	v_mov_b32_e32 v156, v2
	v_mov_b32_e32 v157, v2
	v_mov_b32_e32 v158, v2
	v_mov_b32_e32 v159, v2
	v_mov_b32_e32 v160, v2
	v_mov_b32_e32 v161, v2
	.p2alignl 6, 3212836864

; template <class Epi, class Sched>
; DI void gemm_phase(int wv, LAS unsigned char* lds, const Gemm g, const Sched& S, const Epi& E) {
;     ...
;         const bool has_next = S.next(ui + 1, nxt);
;         const char* nA = has_next ? (const char*)g.A + (size_t)nxt.pm * tstepA : cA; const char* nB = has_next ? (const char*)g.Bt + (size_t)nxt.pn * tstepB : cB;
;     ...
; #pragma unroll
;         for (int a = 0; a < 2; ++a)
; #pragma unroll
;             for (int b = 0; b < 2; ++b)
; #pragma unroll
;                 for (int m = 0; m < 4; ++m)
; #pragma unroll
;                     for (int n = 0; n < 2; ++n) acc[a][b][m][n] = (f32x4){0.f, 0.f, 0.f, 0.f};
.LBB0_2727:
	s_ashr_i32 s13, s12, 31
	s_lshl_b64 s[16:17], s[12:13], 17
	s_add_u32 s16, s48, s16
	s_addc_u32 s17, s49, s17
	s_and_b64 s[22:23], s[22:23], exec
	v_mov_b32_e32 v2, 0
	s_cselect_b32 s13, s17, s3
	s_cselect_b32 s21, s16, s2
	s_mov_b64 s[24:25], 0
	s_mov_b64 s[22:23], -1
	s_mov_b64 s[26:27], 0
	v_mov_b32_e32 v3, v2
	v_mov_b32_e32 v4, v2
	v_mov_b32_e32 v5, v2
	v_mov_b32_e32 v6, v2
	v_mov_b32_e32 v7, v2
	v_mov_b32_e32 v8, v2
	v_mov_b32_e32 v9, v2
	v_mov_b32_e32 v14, v2
	v_mov_b32_e32 v15, v2
	v_mov_b32_e32 v16, v2
	v_mov_b32_e32 v17, v2
	v_mov_b32_e32 v22, v2
	v_mov_b32_e32 v23, v2
	v_mov_b32_e32 v24, v2
	v_mov_b32_e32 v25, v2
	v_mov_b32_e32 v30, v2
	v_mov_b32_e32 v31, v2
	v_mov_b32_e32 v32, v2
	v_mov_b32_e32 v33, v2
	v_mov_b32_e32 v38, v2
	v_mov_b32_e32 v39, v2
	v_mov_b32_e32 v40, v2
	v_mov_b32_e32 v41, v2
	v_mov_b32_e32 v46, v2
	v_mov_b32_e32 v47, v2
	v_mov_b32_e32 v48, v2
	v_mov_b32_e32 v49, v2
	v_mov_b32_e32 v54, v2
	v_mov_b32_e32 v55, v2
	v_mov_b32_e32 v56, v2
	v_mov_b32_e32 v57, v2
	v_mov_b32_e32 v10, v2
	v_mov_b32_e32 v11, v2
	v_mov_b32_e32 v12, v2
	v_mov_b32_e32 v13, v2
	v_mov_b32_e32 v18, v2
	v_mov_b32_e32 v19, v2
	v_mov_b32_e32 v20, v2
	v_mov_b32_e32 v21, v2
	v_mov_b32_e32 v26, v2
	v_mov_b32_e32 v27, v2
	v_mov_b32_e32 v28, v2
	v_mov_b32_e32 v29, v2
	v_mov_b32_e32 v34, v2
	v_mov_b32_e32 v35, v2
	v_mov_b32_e32 v36, v2
	v_mov_b32_e32 v37, v2
	v_mov_b32_e32 v42, v2
	v_mov_b32_e32 v43, v2
	v_mov_b32_e32 v44, v2
	v_mov_b32_e32 v45, v2
	v_mov_b32_e32 v50, v2
	v_mov_b32_e32 v51, v2
	v_mov_b32_e32 v52, v2
	v_mov_b32_e32 v53, v2
	v_mov_b32_e32 v58, v2
	v_mov_b32_e32 v59, v2
	v_mov_b32_e32 v60, v2
	v_mov_b32_e32 v61, v2
	v_mov_b32_e32 v62, v2
	v_mov_b32_e32 v63, v2
	v_mov_b32_e32 v64, v2
	v_mov_b32_e32 v65, v2
	v_mov_b32_e32 v66, v2
	v_mov_b32_e32 v67, v2
	v_mov_b32_e32 v68, v2
	v_mov_b32_e32 v69, v2
	v_mov_b32_e32 v70, v2
	v_mov_b32_e32 v71, v2
	v_mov_b32_e32 v72, v2
	v_mov_b32_e32 v73, v2
	v_mov_b32_e32 v78, v2
	v_mov_b32_e32 v79, v2
	v_mov_b32_e32 v80, v2
	v_mov_b32_e32 v81, v2
	v_mov_b32_e32 v86, v2
	v_mov_b32_e32 v87, v2
	v_mov_b32_e32 v88, v2
	v_mov_b32_e32 v89, v2
	v_mov_b32_e32 v94, v2
	v_mov_b32_e32 v95, v2
	v_mov_b32_e32 v96, v2
	v_mov_b32_e32 v97, v2
	v_mov_b32_e32 v102, v2
	v_mov_b32_e32 v103, v2
	v_mov_b32_e32 v104, v2
	v_mov_b32_e32 v105, v2
	v_mov_b32_e32 v110, v2
	v_mov_b32_e32 v111, v2
	v_mov_b32_e32 v112, v2
	v_mov_b32_e32 v113, v2
	v_mov_b32_e32 v118, v2
	v_mov_b32_e32 v119, v2
	v_mov_b32_e32 v120, v2
	v_mov_b32_e32 v121, v2
	v_mov_b32_e32 v74, v2
	v_mov_b32_e32 v75, v2
	v_mov_b32_e32 v76, v2
	v_mov_b32_e32 v77, v2
	v_mov_b32_e32 v82, v2
	v_mov_b32_e32 v83, v2
	v_mov_b32_e32 v84, v2
	v_mov_b32_e32 v85, v2
	v_mov_b32_e32 v90, v2
	v_mov_b32_e32 v91, v2
	v_mov_b32_e32 v92, v2
	v_mov_b32_e32 v93, v2
	v_mov_b32_e32 v98, v2
	v_mov_b32_e32 v99, v2
	v_mov_b32_e32 v100, v2
	v_mov_b32_e32 v101, v2
	v_mov_b32_e32 v106, v2
	v_mov_b32_e32 v107, v2
	v_mov_b32_e32 v108, v2
	v_mov_b32_e32 v109, v2
	v_mov_b32_e32 v114, v2
	v_mov_b32_e32 v115, v2
	v_mov_b32_e32 v116, v2
	v_mov_b32_e32 v117, v2
	v_mov_b32_e32 v122, v2
	v_mov_b32_e32 v123, v2
	v_mov_b32_e32 v124, v2
	v_mov_b32_e32 v125, v2
	v_mov_b32_e32 v126, v2
	v_mov_b32_e32 v127, v2
	v_mov_b32_e32 v128, v2
	v_mov_b32_e32 v129, v2
	.p2alignl 6, 3212836864

; template <class Epi, class Sched>
; DI void gemm_phase(int wv, LAS unsigned char* lds, const Gemm g, const Sched& S, const Epi& E) {
;     ...
;         const bool has_next = S.next(ui + 1, nxt);
;         const char* nA = has_next ? (const char*)g.A + (size_t)nxt.pm * tstepA : cA; const char* nB = has_next ? (const char*)g.Bt + (size_t)nxt.pn * tstepB : cB;
;     ...
; #pragma unroll
;         for (int a = 0; a < 2; ++a)
; #pragma unroll
;             for (int b = 0; b < 2; ++b)
; #pragma unroll
;                 for (int m = 0; m < 4; ++m)
; #pragma unroll
;                     for (int n = 0; n < 2; ++n) acc[a][b][m][n] = (f32x4){0.f, 0.f, 0.f, 0.f};
.LBB0_2752:
	s_ashr_i32 s15, s14, 31
	s_lshl_b64 s[18:19], s[14:15], 17
	s_add_u32 s18, s54, s18
	s_addc_u32 s19, s55, s19
	s_and_b64 s[26:27], s[26:27], exec
	v_mov_b32_e32 v2, 0
	s_cselect_b32 s15, s19, s21
	s_cselect_b32 s23, s18, s20
	s_mov_b64 s[28:29], 0
	s_mov_b64 s[26:27], -1
	s_mov_b64 s[30:31], 0
	v_mov_b32_e32 v3, v2
	v_mov_b32_e32 v4, v2
	v_mov_b32_e32 v5, v2
	v_mov_b32_e32 v6, v2
	v_mov_b32_e32 v7, v2
	v_mov_b32_e32 v8, v2
	v_mov_b32_e32 v9, v2
	v_mov_b32_e32 v10, v2
	v_mov_b32_e32 v11, v2
	v_mov_b32_e32 v12, v2
	v_mov_b32_e32 v13, v2
	v_mov_b32_e32 v14, v2
	v_mov_b32_e32 v15, v2
	v_mov_b32_e32 v16, v2
	v_mov_b32_e32 v17, v2
	v_mov_b32_e32 v18, v2
	v_mov_b32_e32 v19, v2
	v_mov_b32_e32 v20, v2
	v_mov_b32_e32 v21, v2
	v_mov_b32_e32 v22, v2
	v_mov_b32_e32 v23, v2
	v_mov_b32_e32 v24, v2
	v_mov_b32_e32 v25, v2
	v_mov_b32_e32 v26, v2
	v_mov_b32_e32 v27, v2
	v_mov_b32_e32 v28, v2
	v_mov_b32_e32 v29, v2
	v_mov_b32_e32 v30, v2
	v_mov_b32_e32 v31, v2
	v_mov_b32_e32 v32, v2
	v_mov_b32_e32 v33, v2
	v_mov_b32_e32 v66, v2
	v_mov_b32_e32 v67, v2
	v_mov_b32_e32 v68, v2
	v_mov_b32_e32 v69, v2
	v_mov_b32_e32 v70, v2
	v_mov_b32_e32 v71, v2
	v_mov_b32_e32 v72, v2
	v_mov_b32_e32 v73, v2
	v_mov_b32_e32 v74, v2
	v_mov_b32_e32 v75, v2
	v_mov_b32_e32 v76, v2
	v_mov_b32_e32 v77, v2
	v_mov_b32_e32 v78, v2
	v_mov_b32_e32 v79, v2
	v_mov_b32_e32 v80, v2
	v_mov_b32_e32 v81, v2
	v_mov_b32_e32 v82, v2
	v_mov_b32_e32 v83, v2
	v_mov_b32_e32 v84, v2
	v_mov_b32_e32 v85, v2
	v_mov_b32_e32 v86, v2
	v_mov_b32_e32 v87, v2
	v_mov_b32_e32 v88, v2
	v_mov_b32_e32 v89, v2
	v_mov_b32_e32 v90, v2
	v_mov_b32_e32 v91, v2
	v_mov_b32_e32 v92, v2
	v_mov_b32_e32 v93, v2
	v_mov_b32_e32 v94, v2
	v_mov_b32_e32 v95, v2
	v_mov_b32_e32 v96, v2
	v_mov_b32_e32 v97, v2
	v_mov_b32_e32 v34, v2
	v_mov_b32_e32 v35, v2
	v_mov_b32_e32 v36, v2
	v_mov_b32_e32 v37, v2
	v_mov_b32_e32 v38, v2
	v_mov_b32_e32 v39, v2
	v_mov_b32_e32 v40, v2
	v_mov_b32_e32 v41, v2
	v_mov_b32_e32 v42, v2
	v_mov_b32_e32 v43, v2
	v_mov_b32_e32 v44, v2
	v_mov_b32_e32 v45, v2
	v_mov_b32_e32 v46, v2
	v_mov_b32_e32 v47, v2
	v_mov_b32_e32 v48, v2
	v_mov_b32_e32 v49, v2
	v_mov_b32_e32 v50, v2
	v_mov_b32_e32 v51, v2
	v_mov_b32_e32 v52, v2
	v_mov_b32_e32 v53, v2
	v_mov_b32_e32 v54, v2
	v_mov_b32_e32 v55, v2
	v_mov_b32_e32 v56, v2
	v_mov_b32_e32 v57, v2
	v_mov_b32_e32 v58, v2
	v_mov_b32_e32 v59, v2
	v_mov_b32_e32 v60, v2
	v_mov_b32_e32 v61, v2
	v_mov_b32_e32 v62, v2
	v_mov_b32_e32 v63, v2
	v_mov_b32_e32 v64, v2
	v_mov_b32_e32 v65, v2
	v_mov_b32_e32 v98, v2
	v_mov_b32_e32 v99, v2
	v_mov_b32_e32 v100, v2
	v_mov_b32_e32 v101, v2
	v_mov_b32_e32 v102, v2
	v_mov_b32_e32 v103, v2
	v_mov_b32_e32 v104, v2
	v_mov_b32_e32 v105, v2
	v_mov_b32_e32 v106, v2
	v_mov_b32_e32 v107, v2
	v_mov_b32_e32 v108, v2
	v_mov_b32_e32 v109, v2
	v_mov_b32_e32 v110, v2
	v_mov_b32_e32 v111, v2
	v_mov_b32_e32 v112, v2
	v_mov_b32_e32 v113, v2
	v_mov_b32_e32 v114, v2
	v_mov_b32_e32 v115, v2
	v_mov_b32_e32 v116, v2
	v_mov_b32_e32 v117, v2
	v_mov_b32_e32 v118, v2
	v_mov_b32_e32 v119, v2
	v_mov_b32_e32 v120, v2
	v_mov_b32_e32 v121, v2
	v_mov_b32_e32 v122, v2
	v_mov_b32_e32 v123, v2
	v_mov_b32_e32 v124, v2
	v_mov_b32_e32 v125, v2
	v_mov_b32_e32 v126, v2
	v_mov_b32_e32 v127, v2
	v_mov_b32_e32 v128, v2
	v_mov_b32_e32 v129, v2
	.p2alignl 6, 3212836864

; #define LAS __attribute__((address_space(3)))
; #define MLA_GLOAD(t) do { const size_t ko = (size_t)(64 * (t)); rk = *(const u32x4*)(gk + ko * 64); if (lo256) rr = *(const u32x4*)(gr + ko * 32); rv = *(const u32x4*)(gv + ko); } while (0)
; #define MLA_LSTORE(buf) do { LAS unsigned char* kb_ = lds + (buf) * TILE; *(LAS u32x4*)(kb_ + (tid >> 3) * KS + (tid & 7) * 16) = rk; \
;         if (lo256) *(LAS u32x4*)(kb_ + (tid >> 2) * KS + 128 + (tid & 3) * 16) = rr; lds_store16_as2x8(kb_ + VOFF + (tid >> 3) * VS + (tid & 7) * 16, rv); } while (0)
; DI void mla_qblock(int wv, int w, LAS unsigned char* lds, const bf16_t* Q, const bf16_t* KN, const bf16_t* KR, const bf16_t* VT, bf16_t* O, size_t tok0, int h, int qb) {
;     ...
;     for (int t = 0; t < nfull; ++t) {
;         const int bn = bi == 2 ? 0 : bi + 1;
;         MLA_LSTORE(bn);
;         if (t + 2 < nt) MLA_GLOAD(t + 2);
;         const LAS unsigned char* kb = lds + bi * TILE;
; #pragma nounroll
.LBB0_2826:
	s_or_b64 exec, exec, s[6:7]
	s_mov_b32 s5, s97
	v_lshl_add_u64 v[2:3], s[4:5], 1, v[192:193]
	flat_load_dwordx4 v[156:159], v[2:3] offset:256
	s_mul_i32 s4, s22, 0x5600
	s_add_i32 s4, s4, 0
	v_add_u32_e32 v206, s4, v184
	v_add3_u32 v210, s4, v191, v197
	s_mov_b32 s48, 0
	s_mov_b64 s[22:23], -1
	s_branch .LBB0_2828
	.p2alignl 6, 3212836864

; #define LAS __attribute__((address_space(3)))
; #define MLA_GLOAD(t) do { const size_t ko = (size_t)(64 * (t)); rk = *(const u32x4*)(gk + ko * 64); if (lo256) rr = *(const u32x4*)(gr + ko * 32); rv = *(const u32x4*)(gv + ko); } while (0)
; #define MLA_LSTORE(buf) do { LAS unsigned char* kb_ = lds + (buf) * TILE; *(LAS u32x4*)(kb_ + (tid >> 3) * KS + (tid & 7) * 16) = rk; \
;         if (lo256) *(LAS u32x4*)(kb_ + (tid >> 2) * KS + 128 + (tid & 3) * 16) = rr; lds_store16_as2x8(kb_ + VOFF + (tid >> 3) * VS + (tid & 7) * 16, rv); } while (0)
; DI void mla_qblock(int wv, int w, LAS unsigned char* lds, const bf16_t* Q, const bf16_t* KN, const bf16_t* KR, const bf16_t* VT, bf16_t* O, size_t tok0, int h, int qb) {
;     ...
;     for (int t = nfull; t < nt; ++t) {
;         const int bn = bi == 2 ? 0 : bi + 1;
;         if (t + 1 < nt) MLA_LSTORE(bn);
;         if (t + 2 < nt) MLA_GLOAD(t + 2);
;         const int k0 = 64 * t;
;         if (k0 <= R0 + 63) {
;             const LAS unsigned char* kb = lds + bi * TILE;
; #pragma nounroll
;             for (int tt = 0; tt < 2; ++tt) {
.LBB0_2858:
	s_mul_i32 s5, s50, 0x5600
	v_cmp_lt_i32_e32 vcc, v223, v222
	s_add_i32 s5, s5, 0
	v_add_u32_e32 v165, s5, v184
	v_cndmask_b32_e32 v0, v207, v223, vcc
	s_mov_b32 s46, 0
	v_lshlrev_b32_e32 v166, 2, v0
	v_add_u32_e32 v167, s5, v191
	v_or_b32_e32 v168, s4, v164
	s_mov_b64 s[22:23], -1
	s_branch .LBB0_2860
	.p2alignl 6, 3212836864

; #define PG8_STAGE(bufoff, gbase, voff) do { const char* _gb = (const char*)(gbase); asm volatile("" : "+s"(_gb)); _Pragma("unroll") for (int _i = 0; _i < 2; ++_i) { \
;         unsigned _vo = (voff)[_i]; asm volatile("" : "+v"(_vo));     \
;         __builtin_amdgcn_global_load_lds((const unsigned*)(_gb + _vo), (LAS unsigned*)(lds + (bufoff) + ldsw + _i * 8192), 16, 0, 0); } } while (0)
; #define PG8_LDA(dst, b, h) do { _Pragma("unroll") for (int m = 0; m < 4; ++m) _Pragma("unroll") for (int k = 0; k < 2; ++k) dst[m][k] = *(const LAS bf16x8*)(lds + PG8_SA(b, h) + aoff + m * 2048 + k * 1024); } while (0)
; #define PG8_LDB(dst, b, h) do { _Pragma("unroll") for (int n = 0; n < 2; ++n) _Pragma("unroll") for (int k = 0; k < 2; ++k) dst[n][k] = *(const LAS bf16x8*)(lds + PG8_SB(b, h) + boff + n * 2048 + k * 1024); } while (0)
; #define PG8_MMA(ai, bj, At, Bt) do { __builtin_amdgcn_s_setprio(1); _Pragma("unroll") for (int m = 0; m < 4; ++m) _Pragma("unroll") for (int n = 0; n < 2; ++n) _Pragma("unroll") for (int k = 0; k < 2; ++k) \
;         acc[ai][bj][m][n] = __builtin_amdgcn_mfma_f32_16x16x32_bf16(Bt[n][k], At[m][k], acc[ai][bj][m][n], 0, 0, 0); __builtin_amdgcn_s_setprio(0); } while (0)
; #define PG8_WAIT_V(n) asm volatile("s_waitcnt vmcnt(" #n ")" ::: "memory")
; #define PG8_WAIT_L(n) asm volatile("s_waitcnt lgkmcnt(" #n ")" ::: "memory")
; #define PG8_BAR __builtin_amdgcn_s_barrier()
; #define PG8_SCHED __builtin_amdgcn_sched_barrier(0)
; template <class Epi, class Sched>
; DI void gemm_phase(int wv, LAS unsigned char* lds, const Gemm g, const Sched& S, const Epi& E) {
;     ...
;         for (int t = 0; t < nt; t += 2) {
;             const bool last = (t == nt - 2);
;             const char* a1 = cA + (size_t)(t + 1) * kstep;
;             const char* a2 = last ? nA : cA + (size_t)(t + 2) * kstep; const char* b2 = last ? nB : cB + (size_t)(t + 2) * kstep;
;             const char* a3 = a2 + kstep; const char* b3 = b2 + kstep;
;             PG8_LDB(B0, 0, 0); PG8_LDB(B1, 0, 1); PG8_SCHED; PG8_LDA(At, 0, 0); PG8_STAGE(PG8_SA(1, 1), a1 + hstepA, voffA);
;             PG8_WAIT_V(8); PG8_WAIT_L(0); PG8_BAR; PG8_MMA(0, 0, At, B0); PG8_MMA(0, 1, At, B1); PG8_BAR; PG8_SCHED;
;             PG8_LDA(At, 0, 1); PG8_STAGE(PG8_SB(0, 0), b2, voffB); PG8_STAGE(PG8_SB(0, 1), b2 + hstepB, voffB); PG8_STAGE(PG8_SA(0, 0), a2, voffA);
.LBB0_2949:
	s_add_u32 s23, s24, 0x100
	s_addc_u32 s65, s25, 0
	s_add_u32 s66, s26, 0x100
	s_addc_u32 s67, s27, 0
	s_mov_b32 s24, 0
	s_waitcnt lgkmcnt(0)
	s_waitcnt vmcnt(0)
	s_add_i32 s84, s24, 2
	s_cmp_eq_u32 s55, s24
	s_cselect_b32 s28, s18, s66
	s_cselect_b32 s29, s19, s67
	s_cselect_b32 s26, s20, s23
	s_cselect_b32 s27, s21, s65
	s_add_u32 s24, s28, 0x80
	s_addc_u32 s25, s29, 0
	s_add_i32 s70, 0, 0x10000
	s_add_i32 s78, 0, 0x14000
	v_add_u32_e32 v142, s70, v175
	v_add_u32_e32 v158, s78, v175
	ds_read_b128 v[130:133], v142
	ds_read_b128 v[134:137], v142 offset:1024
	ds_read_b128 v[138:141], v142 offset:2048
	ds_read_b128 v[142:145], v142 offset:3072
	ds_read_b128 v[146:149], v158
	ds_read_b128 v[150:153], v158 offset:1024
	ds_read_b128 v[154:157], v158 offset:2048
	ds_read_b128 v[158:161], v158 offset:3072
	s_add_u32 s30, s66, s36
	s_addc_u32 s31, s67, 0
	s_add_u32 s30, s30, 0xffffff80
	s_addc_u32 s31, s31, -1
	v_mov_b32_e32 v170, v0
	ds_read_b128 v[162:165], v176
	ds_read_b128 v[166:169], v176 offset:1024
	ds_read_b128 v[178:181], v176 offset:2048
	ds_read_b128 v[182:185], v176 offset:3072
	ds_read_b128 v[186:189], v176 offset:4096
	ds_read_b128 v[190:193], v176 offset:5120
	ds_read_b128 v[194:197], v176 offset:6144
	ds_read_b128 v[198:201], v176 offset:7168
	s_add_i32 m0, s39, 0xc000
	s_nop 0
	global_load_lds_dwordx4 v170, s[30:31]
	v_mov_b32_e32 v170, v173
	s_add_i32 m0, s39, 0xe000
	s_nop 0
	global_load_lds_dwordx4 v170, s[30:31]
	s_waitcnt vmcnt(8)
	s_waitcnt lgkmcnt(0)
	s_barrier
	s_setprio 1
	s_waitcnt lgkmcnt(0)
	v_mfma_f32_16x16x32_bf16 v[126:129], v[130:133], v[162:165], 0
	v_mfma_f32_16x16x32_bf16 v[122:125], v[138:141], v[162:165], 0
	v_mfma_f32_16x16x32_bf16 v[110:113], v[130:133], v[178:181], 0
	v_mfma_f32_16x16x32_bf16 v[106:109], v[138:141], v[178:181], 0
	v_mfma_f32_16x16x32_bf16 v[94:97], v[130:133], v[186:189], 0
	v_mfma_f32_16x16x32_bf16 v[90:93], v[138:141], v[186:189], 0
	v_mfma_f32_16x16x32_bf16 v[78:81], v[130:133], v[194:197], 0
	v_mfma_f32_16x16x32_bf16 v[74:77], v[138:141], v[194:197], 0
	v_mfma_f32_16x16x32_bf16 v[126:129], v[134:137], v[166:169], v[126:129]
	v_mfma_f32_16x16x32_bf16 v[122:125], v[142:145], v[166:169], v[122:125]
	v_mfma_f32_16x16x32_bf16 v[110:113], v[134:137], v[182:185], v[110:113]
	v_mfma_f32_16x16x32_bf16 v[106:109], v[142:145], v[182:185], v[106:109]
	v_mfma_f32_16x16x32_bf16 v[94:97], v[134:137], v[190:193], v[94:97]
	v_mfma_f32_16x16x32_bf16 v[90:93], v[142:145], v[190:193], v[90:93]
	v_mfma_f32_16x16x32_bf16 v[78:81], v[134:137], v[198:201], v[78:81]
	v_mfma_f32_16x16x32_bf16 v[74:77], v[142:145], v[198:201], v[74:77]
	s_setprio 0
	s_setprio 1
	v_mfma_f32_16x16x32_bf16 v[118:121], v[146:149], v[162:165], 0
	v_mfma_f32_16x16x32_bf16 v[114:117], v[154:157], v[162:165], 0
	v_mfma_f32_16x16x32_bf16 v[102:105], v[146:149], v[178:181], 0
	v_mfma_f32_16x16x32_bf16 v[98:101], v[154:157], v[178:181], 0
	v_mfma_f32_16x16x32_bf16 v[86:89], v[146:149], v[186:189], 0
	v_mfma_f32_16x16x32_bf16 v[82:85], v[154:157], v[186:189], 0
	v_mfma_f32_16x16x32_bf16 v[70:73], v[146:149], v[194:197], 0
	v_mfma_f32_16x16x32_bf16 v[66:69], v[154:157], v[194:197], 0
	v_mfma_f32_16x16x32_bf16 v[118:121], v[150:153], v[166:169], v[118:121]
	v_mfma_f32_16x16x32_bf16 v[114:117], v[158:161], v[166:169], v[114:117]
	v_mfma_f32_16x16x32_bf16 v[102:105], v[150:153], v[182:185], v[102:105]
	v_mfma_f32_16x16x32_bf16 v[98:101], v[158:161], v[182:185], v[98:101]
	v_mfma_f32_16x16x32_bf16 v[86:89], v[150:153], v[190:193], v[86:89]
	v_mfma_f32_16x16x32_bf16 v[82:85], v[158:161], v[190:193], v[82:85]
	v_mfma_f32_16x16x32_bf16 v[70:73], v[150:153], v[198:201], v[70:73]
	v_mfma_f32_16x16x32_bf16 v[66:69], v[158:161], v[198:201], v[66:69]
	s_setprio 0
	s_barrier
	s_mov_b64 s[30:31], s[26:27]
	v_mov_b32_e32 v170, v172
	s_add_i32 s70, s70, s38
	ds_read_b128 v[162:165], v176 offset:16384
	ds_read_b128 v[166:169], v176 offset:17408
	ds_read_b128 v[178:181], v176 offset:18432
	ds_read_b128 v[182:185], v176 offset:19456
	ds_read_b128 v[186:189], v176 offset:20480
	ds_read_b128 v[190:193], v176 offset:21504
	ds_read_b128 v[194:197], v176 offset:22528
	ds_read_b128 v[198:201], v176 offset:23552
	s_mov_b32 m0, s70
	s_nop 0
	global_load_lds_dwordx4 v170, s[30:31]
	v_mov_b32_e32 v170, v174
	s_add_i32 m0, s70, 0x2000
	s_nop 0
	global_load_lds_dwordx4 v170, s[30:31]
	s_add_u32 s30, s26, s36
	s_addc_u32 s31, s27, 0
	s_mov_b64 s[70:71], s[30:31]
	v_mov_b32_e32 v170, v172
	s_add_i32 s78, s78, s38
	s_mov_b32 m0, s78
	s_nop 0
	global_load_lds_dwordx4 v170, s[70:71]
	v_mov_b32_e32 v170, v174
	s_add_i32 m0, s78, 0x2000
	s_nop 0
	global_load_lds_dwordx4 v170, s[70:71]
	s_mov_b64 s[70:71], s[28:29]
	v_mov_b32_e32 v170, v0
	s_mov_b32 m0, s39
	s_nop 0
	global_load_lds_dwordx4 v170, s[70:71]
	v_mov_b32_e32 v170, v173
	s_mov_b32 m0, s44
	s_nop 0
	global_load_lds_dwordx4 v170, s[70:71]
	s_waitcnt vmcnt(8)
	s_waitcnt lgkmcnt(0)
	s_barrier
; #define PG8_STAGE(bufoff, gbase, voff) do { const char* _gb = (const char*)(gbase); asm volatile("" : "+s"(_gb)); _Pragma("unroll") for (int _i = 0; _i < 2; ++_i) { \
;         unsigned _vo = (voff)[_i]; asm volatile("" : "+v"(_vo));     \
;         __builtin_amdgcn_global_load_lds((const unsigned*)(_gb + _vo), (LAS unsigned*)(lds + (bufoff) + ldsw + _i * 8192), 16, 0, 0); } } while (0)
; #define PG8_LDA(dst, b, h) do { _Pragma("unroll") for (int m = 0; m < 4; ++m) _Pragma("unroll") for (int k = 0; k < 2; ++k) dst[m][k] = *(const LAS bf16x8*)(lds + PG8_SA(b, h) + aoff + m * 2048 + k * 1024); } while (0)
; #define PG8_LDB(dst, b, h) do { _Pragma("unroll") for (int n = 0; n < 2; ++n) _Pragma("unroll") for (int k = 0; k < 2; ++k) dst[n][k] = *(const LAS bf16x8*)(lds + PG8_SB(b, h) + boff + n * 2048 + k * 1024); } while (0)
; #define PG8_MMA(ai, bj, At, Bt) do { __builtin_amdgcn_s_setprio(1); _Pragma("unroll") for (int m = 0; m < 4; ++m) _Pragma("unroll") for (int n = 0; n < 2; ++n) _Pragma("unroll") for (int k = 0; k < 2; ++k) \
;         acc[ai][bj][m][n] = __builtin_amdgcn_mfma_f32_16x16x32_bf16(Bt[n][k], At[m][k], acc[ai][bj][m][n], 0, 0, 0); __builtin_amdgcn_s_setprio(0); } while (0)
; #define PG8_WAIT_V(n) asm volatile("s_waitcnt vmcnt(" #n ")" ::: "memory")
; #define PG8_WAIT_L(n) asm volatile("s_waitcnt lgkmcnt(" #n ")" ::: "memory")
; #define PG8_BAR __builtin_amdgcn_s_barrier()
; #define PG8_SCHED __builtin_amdgcn_sched_barrier(0)
; template <class Epi, class Sched>
; DI void gemm_phase(int wv, LAS unsigned char* lds, const Gemm g, const Sched& S, const Epi& E) {
;     ...
;             PG8_WAIT_V(8); PG8_WAIT_L(0); PG8_BAR; PG8_MMA(1, 0, At, B0); PG8_MMA(1, 1, At, B1); PG8_BAR; PG8_SCHED;
;             PG8_LDB(B0, 1, 0); PG8_LDB(B1, 1, 1); PG8_SCHED; PG8_LDA(At, 1, 0); PG8_STAGE(PG8_SA(0, 1), a2 + hstepA, voffA);
;             PG8_WAIT_V(8); PG8_WAIT_L(0); PG8_BAR; PG8_MMA(0, 0, At, B0); PG8_MMA(0, 1, At, B1); PG8_BAR; PG8_SCHED;
	s_setprio 1
	s_waitcnt lgkmcnt(0)
	v_mfma_f32_16x16x32_bf16 v[62:65], v[130:133], v[162:165], 0
	v_mfma_f32_16x16x32_bf16 v[58:61], v[138:141], v[162:165], 0
	v_mfma_f32_16x16x32_bf16 v[46:49], v[130:133], v[178:181], 0
	v_mfma_f32_16x16x32_bf16 v[42:45], v[138:141], v[178:181], 0
	v_mfma_f32_16x16x32_bf16 v[30:33], v[130:133], v[186:189], 0
	v_mfma_f32_16x16x32_bf16 v[26:29], v[138:141], v[186:189], 0
	v_mfma_f32_16x16x32_bf16 v[14:17], v[130:133], v[194:197], 0
	v_mfma_f32_16x16x32_bf16 v[10:13], v[138:141], v[194:197], 0
	v_mfma_f32_16x16x32_bf16 v[62:65], v[134:137], v[166:169], v[62:65]
	v_mfma_f32_16x16x32_bf16 v[58:61], v[142:145], v[166:169], v[58:61]
	v_mfma_f32_16x16x32_bf16 v[46:49], v[134:137], v[182:185], v[46:49]
	v_mfma_f32_16x16x32_bf16 v[42:45], v[142:145], v[182:185], v[42:45]
	v_mfma_f32_16x16x32_bf16 v[30:33], v[134:137], v[190:193], v[30:33]
	v_mfma_f32_16x16x32_bf16 v[26:29], v[142:145], v[190:193], v[26:29]
	v_mfma_f32_16x16x32_bf16 v[14:17], v[134:137], v[198:201], v[14:17]
	v_mfma_f32_16x16x32_bf16 v[10:13], v[142:145], v[198:201], v[10:13]
	s_setprio 0
	s_setprio 1
	v_mfma_f32_16x16x32_bf16 v[54:57], v[146:149], v[162:165], 0
	v_mfma_f32_16x16x32_bf16 v[50:53], v[154:157], v[162:165], 0
	v_mfma_f32_16x16x32_bf16 v[38:41], v[146:149], v[178:181], 0
	v_mfma_f32_16x16x32_bf16 v[34:37], v[154:157], v[178:181], 0
	v_mfma_f32_16x16x32_bf16 v[22:25], v[146:149], v[186:189], 0
	v_mfma_f32_16x16x32_bf16 v[18:21], v[154:157], v[186:189], 0
	v_mfma_f32_16x16x32_bf16 v[6:9], v[146:149], v[194:197], 0
	v_mfma_f32_16x16x32_bf16 v[2:5], v[154:157], v[194:197], 0
	v_mfma_f32_16x16x32_bf16 v[54:57], v[150:153], v[166:169], v[54:57]
	v_mfma_f32_16x16x32_bf16 v[50:53], v[158:161], v[166:169], v[50:53]
	v_mfma_f32_16x16x32_bf16 v[38:41], v[150:153], v[182:185], v[38:41]
	v_mfma_f32_16x16x32_bf16 v[34:37], v[158:161], v[182:185], v[34:37]
	v_mfma_f32_16x16x32_bf16 v[22:25], v[150:153], v[190:193], v[22:25]
	v_mfma_f32_16x16x32_bf16 v[18:21], v[158:161], v[190:193], v[18:21]
	v_mfma_f32_16x16x32_bf16 v[6:9], v[150:153], v[198:201], v[6:9]
	v_mfma_f32_16x16x32_bf16 v[2:5], v[158:161], v[198:201], v[2:5]
	s_setprio 0
	s_barrier
	s_add_i32 s70, 0, 0x18000
	s_add_i32 s71, 0, 0x1c000
	v_add_u32_e32 v142, s70, v175
	v_add_u32_e32 v158, s71, v175
	ds_read_b128 v[130:133], v142
	ds_read_b128 v[134:137], v142 offset:1024
	ds_read_b128 v[138:141], v142 offset:2048
	ds_read_b128 v[142:145], v142 offset:3072
	ds_read_b128 v[146:149], v158
	ds_read_b128 v[150:153], v158 offset:1024
	ds_read_b128 v[154:157], v158 offset:2048
	ds_read_b128 v[158:161], v158 offset:3072
	s_add_u32 s28, s28, s36
	s_addc_u32 s29, s29, 0
	v_mov_b32_e32 v170, v0
	s_mov_b32 m0, s45
	ds_read_b128 v[162:165], v176 offset:32768
	ds_read_b128 v[166:169], v176 offset:33792
	ds_read_b128 v[178:181], v176 offset:34816
	ds_read_b128 v[182:185], v176 offset:35840
	ds_read_b128 v[186:189], v176 offset:36864
	ds_read_b128 v[190:193], v176 offset:37888
	ds_read_b128 v[194:197], v176 offset:38912
	ds_read_b128 v[198:201], v176 offset:39936
	s_nop 0
	global_load_lds_dwordx4 v170, s[28:29]
	v_mov_b32_e32 v170, v173
	s_mov_b32 m0, s46
	s_nop 0
	global_load_lds_dwordx4 v170, s[28:29]
	s_waitcnt vmcnt(8)
	s_waitcnt lgkmcnt(0)
	s_barrier
	s_setprio 1
	s_waitcnt lgkmcnt(0)
	v_mfma_f32_16x16x32_bf16 v[126:129], v[130:133], v[162:165], v[126:129]
	v_mfma_f32_16x16x32_bf16 v[122:125], v[138:141], v[162:165], v[122:125]
	v_mfma_f32_16x16x32_bf16 v[110:113], v[130:133], v[178:181], v[110:113]
	v_mfma_f32_16x16x32_bf16 v[106:109], v[138:141], v[178:181], v[106:109]
	v_mfma_f32_16x16x32_bf16 v[94:97], v[130:133], v[186:189], v[94:97]
	v_mfma_f32_16x16x32_bf16 v[90:93], v[138:141], v[186:189], v[90:93]
	v_mfma_f32_16x16x32_bf16 v[78:81], v[130:133], v[194:197], v[78:81]
	v_mfma_f32_16x16x32_bf16 v[74:77], v[138:141], v[194:197], v[74:77]
	v_mfma_f32_16x16x32_bf16 v[126:129], v[134:137], v[166:169], v[126:129]
	v_mfma_f32_16x16x32_bf16 v[122:125], v[142:145], v[166:169], v[122:125]
	v_mfma_f32_16x16x32_bf16 v[110:113], v[134:137], v[182:185], v[110:113]
	v_mfma_f32_16x16x32_bf16 v[106:109], v[142:145], v[182:185], v[106:109]
	v_mfma_f32_16x16x32_bf16 v[94:97], v[134:137], v[190:193], v[94:97]
	v_mfma_f32_16x16x32_bf16 v[90:93], v[142:145], v[190:193], v[90:93]
	v_mfma_f32_16x16x32_bf16 v[78:81], v[134:137], v[198:201], v[78:81]
	v_mfma_f32_16x16x32_bf16 v[74:77], v[142:145], v[198:201], v[74:77]
	s_setprio 0
	s_setprio 1
	v_mfma_f32_16x16x32_bf16 v[118:121], v[146:149], v[162:165], v[118:121]
	v_mfma_f32_16x16x32_bf16 v[114:117], v[154:157], v[162:165], v[114:117]
	v_mfma_f32_16x16x32_bf16 v[102:105], v[146:149], v[178:181], v[102:105]
	v_mfma_f32_16x16x32_bf16 v[98:101], v[154:157], v[178:181], v[98:101]
	v_mfma_f32_16x16x32_bf16 v[86:89], v[146:149], v[186:189], v[86:89]
	v_mfma_f32_16x16x32_bf16 v[82:85], v[154:157], v[186:189], v[82:85]
	v_mfma_f32_16x16x32_bf16 v[70:73], v[146:149], v[194:197], v[70:73]
	v_mfma_f32_16x16x32_bf16 v[66:69], v[154:157], v[194:197], v[66:69]
	v_mfma_f32_16x16x32_bf16 v[118:121], v[150:153], v[166:169], v[118:121]
	v_mfma_f32_16x16x32_bf16 v[114:117], v[158:161], v[166:169], v[114:117]
	v_mfma_f32_16x16x32_bf16 v[102:105], v[150:153], v[182:185], v[102:105]
	v_mfma_f32_16x16x32_bf16 v[98:101], v[158:161], v[182:185], v[98:101]
	v_mfma_f32_16x16x32_bf16 v[86:89], v[150:153], v[190:193], v[86:89]
	v_mfma_f32_16x16x32_bf16 v[82:85], v[158:161], v[190:193], v[82:85]
	v_mfma_f32_16x16x32_bf16 v[70:73], v[150:153], v[198:201], v[70:73]
	v_mfma_f32_16x16x32_bf16 v[66:69], v[158:161], v[198:201], v[66:69]
	s_setprio 0
	s_barrier
; #define PG8_STAGE(bufoff, gbase, voff) do { const char* _gb = (const char*)(gbase); asm volatile("" : "+s"(_gb)); _Pragma("unroll") for (int _i = 0; _i < 2; ++_i) { \
;         unsigned _vo = (voff)[_i]; asm volatile("" : "+v"(_vo));     \
;         __builtin_amdgcn_global_load_lds((const unsigned*)(_gb + _vo), (LAS unsigned*)(lds + (bufoff) + ldsw + _i * 8192), 16, 0, 0); } } while (0)
; #define PG8_LDA(dst, b, h) do { _Pragma("unroll") for (int m = 0; m < 4; ++m) _Pragma("unroll") for (int k = 0; k < 2; ++k) dst[m][k] = *(const LAS bf16x8*)(lds + PG8_SA(b, h) + aoff + m * 2048 + k * 1024); } while (0)
; #define PG8_LDB(dst, b, h) do { _Pragma("unroll") for (int n = 0; n < 2; ++n) _Pragma("unroll") for (int k = 0; k < 2; ++k) dst[n][k] = *(const LAS bf16x8*)(lds + PG8_SB(b, h) + boff + n * 2048 + k * 1024); } while (0)
; #define PG8_WAIT_V(n) asm volatile("s_waitcnt vmcnt(" #n ")" ::: "memory")
; #define PG8_BAR __builtin_amdgcn_s_barrier()
; template <class Epi, class Sched>
; DI void gemm_phase(int wv, LAS unsigned char* lds, const Gemm g, const Sched& S, const Epi& E) {
;     ...
;             const char* a1 = cA + (size_t)(t + 1) * kstep;
;             const char* a2 = last ? nA : cA + (size_t)(t + 2) * kstep; const char* b2 = last ? nB : cB + (size_t)(t + 2) * kstep;
;             const char* a3 = a2 + kstep; const char* b3 = b2 + kstep;
;             PG8_LDB(B0, 0, 0); PG8_LDB(B1, 0, 1); PG8_SCHED; PG8_LDA(At, 0, 0); PG8_STAGE(PG8_SA(1, 1), a1 + hstepA, voffA);
;             PG8_WAIT_V(8); PG8_WAIT_L(0); PG8_BAR; PG8_MMA(0, 0, At, B0); PG8_MMA(0, 1, At, B1); PG8_BAR; PG8_SCHED;
;             PG8_LDA(At, 0, 1); PG8_STAGE(PG8_SB(0, 0), b2, voffB); PG8_STAGE(PG8_SB(0, 1), b2 + hstepB, voffB); PG8_STAGE(PG8_SA(0, 0), a2, voffA);
;             PG8_WAIT_V(8); PG8_WAIT_L(0); PG8_BAR; PG8_MMA(1, 0, At, B0); PG8_MMA(1, 1, At, B1); PG8_BAR; PG8_SCHED;
;             PG8_LDB(B0, 1, 0); PG8_LDB(B1, 1, 1); PG8_SCHED; PG8_LDA(At, 1, 0); PG8_STAGE(PG8_SA(0, 1), a2 + hstepA, voffA);
;             PG8_WAIT_V(8); PG8_WAIT_L(0); PG8_BAR; PG8_MMA(0, 0, At, B0); PG8_MMA(0, 1, At, B1); PG8_BAR; PG8_SCHED;
;             PG8_LDA(At, 1, 1); PG8_STAGE(PG8_SB(1, 0), b3, voffB); PG8_STAGE(PG8_SB(1, 1), b3 + hstepB, voffB); PG8_STAGE(PG8_SA(1, 0), a3, voffA);
;             PG8_WAIT_V(8); PG8_WAIT_L(0); PG8_BAR; PG8_MMA(1, 0, At, B0); PG8_MMA(1, 1, At, B1); PG8_BAR; PG8_SCHED;
	s_add_u32 s26, s26, 0x80
	s_addc_u32 s27, s27, 0
	v_mov_b32_e32 v170, v172
	s_add_i32 s28, s70, s38
	ds_read_b128 v[162:165], v176 offset:49152
	ds_read_b128 v[166:169], v176 offset:50176
	ds_read_b128 v[178:181], v176 offset:51200
	ds_read_b128 v[182:185], v176 offset:52224
	ds_read_b128 v[186:189], v176 offset:53248
	ds_read_b128 v[190:193], v176 offset:54272
	ds_read_b128 v[194:197], v176 offset:55296
	ds_read_b128 v[198:201], v176 offset:56320
	s_mov_b32 m0, s28
	s_nop 0
	global_load_lds_dwordx4 v170, s[26:27]
	v_mov_b32_e32 v170, v174
	s_add_i32 m0, s28, 0x2000
	s_nop 0
	global_load_lds_dwordx4 v170, s[26:27]
	s_add_u32 s26, s30, 0x80
	s_addc_u32 s27, s31, 0
	v_mov_b32_e32 v170, v172
	s_add_i32 s28, s71, s38
	s_mov_b32 m0, s28
	s_nop 0
	global_load_lds_dwordx4 v170, s[26:27]
	v_mov_b32_e32 v170, v174
	s_add_i32 m0, s28, 0x2000
	s_nop 0
	global_load_lds_dwordx4 v170, s[26:27]
	v_mov_b32_e32 v170, v0
	s_mov_b32 m0, s51
	s_nop 0
	global_load_lds_dwordx4 v170, s[24:25]
	v_mov_b32_e32 v170, v173
	s_mov_b32 m0, s54
	s_nop 0
	global_load_lds_dwordx4 v170, s[24:25]
	s_waitcnt vmcnt(8)
	s_waitcnt lgkmcnt(0)
	s_barrier
	s_setprio 1
	s_waitcnt lgkmcnt(0)
	v_mfma_f32_16x16x32_bf16 v[62:65], v[130:133], v[162:165], v[62:65]
	v_mfma_f32_16x16x32_bf16 v[58:61], v[138:141], v[162:165], v[58:61]
	v_mfma_f32_16x16x32_bf16 v[46:49], v[130:133], v[178:181], v[46:49]
	v_mfma_f32_16x16x32_bf16 v[42:45], v[138:141], v[178:181], v[42:45]
	v_mfma_f32_16x16x32_bf16 v[30:33], v[130:133], v[186:189], v[30:33]
	v_mfma_f32_16x16x32_bf16 v[26:29], v[138:141], v[186:189], v[26:29]
	v_mfma_f32_16x16x32_bf16 v[14:17], v[130:133], v[194:197], v[14:17]
	v_mfma_f32_16x16x32_bf16 v[10:13], v[138:141], v[194:197], v[10:13]
	v_mfma_f32_16x16x32_bf16 v[62:65], v[134:137], v[166:169], v[62:65]
	v_mfma_f32_16x16x32_bf16 v[58:61], v[142:145], v[166:169], v[58:61]
	v_mfma_f32_16x16x32_bf16 v[46:49], v[134:137], v[182:185], v[46:49]
	v_mfma_f32_16x16x32_bf16 v[42:45], v[142:145], v[182:185], v[42:45]
	v_mfma_f32_16x16x32_bf16 v[30:33], v[134:137], v[190:193], v[30:33]
	v_mfma_f32_16x16x32_bf16 v[26:29], v[142:145], v[190:193], v[26:29]
	v_mfma_f32_16x16x32_bf16 v[14:17], v[134:137], v[198:201], v[14:17]
	v_mfma_f32_16x16x32_bf16 v[10:13], v[142:145], v[198:201], v[10:13]
	s_setprio 0
	s_setprio 1
	v_mfma_f32_16x16x32_bf16 v[54:57], v[146:149], v[162:165], v[54:57]
	v_mfma_f32_16x16x32_bf16 v[50:53], v[154:157], v[162:165], v[50:53]
	v_mfma_f32_16x16x32_bf16 v[38:41], v[146:149], v[178:181], v[38:41]
	v_mfma_f32_16x16x32_bf16 v[34:37], v[154:157], v[178:181], v[34:37]
	v_mfma_f32_16x16x32_bf16 v[22:25], v[146:149], v[186:189], v[22:25]
	v_mfma_f32_16x16x32_bf16 v[18:21], v[154:157], v[186:189], v[18:21]
	v_mfma_f32_16x16x32_bf16 v[6:9], v[146:149], v[194:197], v[6:9]
	v_mfma_f32_16x16x32_bf16 v[2:5], v[154:157], v[194:197], v[2:5]
	v_mfma_f32_16x16x32_bf16 v[54:57], v[150:153], v[166:169], v[54:57]
	v_mfma_f32_16x16x32_bf16 v[50:53], v[158:161], v[166:169], v[50:53]
	v_mfma_f32_16x16x32_bf16 v[38:41], v[150:153], v[182:185], v[38:41]
	v_mfma_f32_16x16x32_bf16 v[34:37], v[158:161], v[182:185], v[34:37]
	v_mfma_f32_16x16x32_bf16 v[22:25], v[150:153], v[190:193], v[22:25]
	v_mfma_f32_16x16x32_bf16 v[18:21], v[158:161], v[190:193], v[18:21]
	v_mfma_f32_16x16x32_bf16 v[6:9], v[150:153], v[198:201], v[6:9]
	v_mfma_f32_16x16x32_bf16 v[2:5], v[158:161], v[198:201], v[2:5]
	s_setprio 0
	s_barrier
	s_add_u32 s23, s23, 0x100
	s_addc_u32 s65, s65, 0
	s_add_u32 s66, s66, 0x100
	s_addc_u32 s67, s67, 0
	s_cmp_ge_u32 s84, s48
	s_mov_b32 s24, s84
	.p2alignl 6, 3212836864
